# as previous + SP2 load segments issue their 4 LDS-DMAs before the 8 ds_reads
# speedup vs baseline: 1.0023x; 1.0008x over previous
; #define PG8_STAGE(bufoff, gbase, voff) do { _Pragma("unroll") for (int _i = 0; _i < 2; ++_i) \
;         __builtin_amdgcn_global_load_lds((const unsigned*)((const char*)(gbase) + (voff)[_i]), (PG8_LAS unsigned*)(lds + (bufoff) + ldsw + _i * 8192), 16, 0, 0); } while (0)
; #define PG8_LDA(dst, b, h) do { _Pragma("unroll") for (int m = 0; m < 4; ++m) _Pragma("unroll") for (int k = 0; k < 2; ++k) dst[m][k] = *(const PG8_LAS bf16x8*)(lds + PG8_SA(b, h) + aoff + m * 2048 + k * 1024); } while (0)
; #define PG8_LDB(dst, b, h) do { _Pragma("unroll") for (int n = 0; n < 2; ++n) _Pragma("unroll") for (int k = 0; k < 2; ++k) dst[n][k] = *(const PG8_LAS bf16x8*)(lds + PG8_SB(b, h) + boff + n * 2048 + k * 1024); } while (0)
; #define PG8_WAIT_V(n) asm volatile("s_waitcnt vmcnt(" #n ")" ::: "memory")
; #define PG8_WAIT_L(n) asm volatile("s_waitcnt lgkmcnt(" #n ")" ::: "memory")
; #define PG8_BAR __builtin_amdgcn_s_barrier()
; #define PG8_SCHED __builtin_amdgcn_sched_barrier(0)
; template <class Epi, class Sched, bool ALIGN_EPI = false, bool SP2 = false>
; __device__ __forceinline__ void gemm_phase(PG8_LAS unsigned char* lds, const Gemm g, const Sched& S, const Epi& E) {
;     ...
;         const bool has_next = S.next(ui + 1, nxt);
;         const char* nA = has_next ? (const char*)g.A + (size_t)nxt.pm * tstep : cA; const char* nB = has_next ? (const char*)g.Bt + (size_t)nxt.pn * tstep : cB;
;         for (int t = 0; t < nt; t += 2) {
;             const bool last = (t == nt - 2);
;             const char* a1 = cA + (size_t)(t + 1) * kstep;
;             const char* a2 = last ? nA : cA + (size_t)(t + 2) * kstep; const char* b2 = last ? nB : cB + (size_t)(t + 2) * kstep;
;             const char* a3 = a2 + kstep; const char* b3 = b2 + kstep;
;             if (last && has_next) S.a_ready(nxt);
;             if constexpr (SP2) {
;             PG8_LDB(B0, 0, 0); PG8_LDB(B1, 0, 1); PG8_SCHED; PG8_LDA(At, 0, 0); PG8_STAGE(PG8_SA(1, 1), a1 + hstep, voffA);
;             PG8_WAIT_V(8); PG8_WAIT_L(0); PG8_BAR; PG8_MMA(0, 0, At, B0); PG8_MMA(0, 1, At, B1); PG8_BAR; PG8_SCHED;
;             PG8_LDA(At, 0, 1); PG8_STAGE(PG8_SB(0, 0), b2, voffB); PG8_STAGE(PG8_SB(0, 1), b2 + hstep, voffB); PG8_STAGE(PG8_SA(0, 0), a2, voffA);
;             PG8_WAIT_V(8); PG8_WAIT_L(0); PG8_BAR; PG8_MMA(1, 0, At, B0); PG8_MMA(1, 1, At, B1); PG8_BAR; PG8_SCHED;
.LBB0_150:
	s_setprio 1
	ds_read_b128 v[144:147], v155
	ds_read_b128 v[148:151], v155 offset:1024
	ds_read_b128 v[160:163], v155 offset:2048
	ds_read_b128 v[164:167], v155 offset:3072
	ds_read_b128 v[168:171], v156
	ds_read_b128 v[172:175], v156 offset:1024
	ds_read_b128 v[176:179], v156 offset:2048
	ds_read_b128 v[180:183], v156 offset:3072
	s_add_u32 s30, s28, 0xfff80080
	s_addc_u32 s31, s29, -1
	s_cmp_eq_u32 s60, 28
	s_cselect_b32 s35, s15, s31
	s_cselect_b32 s34, s56, s30
	s_cselect_b32 s31, s13, s59
	s_cselect_b32 s30, s57, s58
	v_lshl_add_u64 v[216:217], s[28:29], 0, v[136:137]
	s_add_i32 m0, s25, 0xc000
	ds_read_b128 v[184:187], v157
	ds_read_b128 v[188:191], v157 offset:1024
	ds_read_b128 v[192:195], v157 offset:2048
	ds_read_b128 v[196:199], v157 offset:3072
	ds_read_b128 v[200:203], v157 offset:4096
	ds_read_b128 v[204:207], v157 offset:5120
	ds_read_b128 v[208:211], v157 offset:6144
	ds_read_b128 v[212:215], v157 offset:7168
	global_load_lds_dwordx4 v[216:217], off
	v_lshl_add_u64 v[216:217], s[28:29], 0, v[138:139]
	s_add_i32 m0, s25, 0xe000
	s_nop 0
	global_load_lds_dwordx4 v[216:217], off
	s_mov_b32 m0, s48
	s_nop 0
	global_load_lds_dwordx4 v[250:251], off
	s_mov_b32 m0, s49
	s_nop 0
	global_load_lds_dwordx4 v[252:253], off
	s_add_u32 s62, s30, 0x80000
	s_addc_u32 s63, s31, 0
	v_lshl_add_u64 v[216:217], s[30:31], 0, v[132:133]
	v_lshl_add_u64 v[218:219], s[30:31], 0, v[128:129]
	v_lshl_add_u64 v[246:247], s[62:63], 0, v[132:133]
	v_lshl_add_u64 v[222:223], s[34:35], 0, v[130:131]
	v_lshl_add_u64 v[248:249], s[62:63], 0, v[128:129]
	v_lshl_add_u64 v[220:221], s[34:35], 0, v[134:135]
	s_waitcnt vmcnt(10)
	s_waitcnt lgkmcnt(0)
	s_setprio 0
	s_barrier
	s_waitcnt lgkmcnt(0)
	v_mfma_f32_16x16x32_bf16 v[124:127], v[144:147], v[184:187], v[124:127]
	v_mfma_f32_16x16x32_bf16 v[120:123], v[160:163], v[184:187], v[120:123]
	v_mfma_f32_16x16x32_bf16 v[108:111], v[144:147], v[192:195], v[108:111]
	v_mfma_f32_16x16x32_bf16 v[104:107], v[160:163], v[192:195], v[104:107]
	v_mfma_f32_16x16x32_bf16 v[92:95], v[144:147], v[200:203], v[92:95]
	v_mfma_f32_16x16x32_bf16 v[88:91], v[160:163], v[200:203], v[88:91]
	v_mfma_f32_16x16x32_bf16 v[76:79], v[144:147], v[208:211], v[76:79]
	v_mfma_f32_16x16x32_bf16 v[72:75], v[160:163], v[208:211], v[72:75]
	v_mfma_f32_16x16x32_bf16 v[124:127], v[148:151], v[188:191], v[124:127]
	v_mfma_f32_16x16x32_bf16 v[120:123], v[164:167], v[188:191], v[120:123]
	v_mfma_f32_16x16x32_bf16 v[108:111], v[148:151], v[196:199], v[108:111]
	v_mfma_f32_16x16x32_bf16 v[104:107], v[164:167], v[196:199], v[104:107]
	v_mfma_f32_16x16x32_bf16 v[92:95], v[148:151], v[204:207], v[92:95]
	v_mfma_f32_16x16x32_bf16 v[88:91], v[164:167], v[204:207], v[88:91]
	v_mfma_f32_16x16x32_bf16 v[76:79], v[148:151], v[212:215], v[76:79]
	v_mfma_f32_16x16x32_bf16 v[72:75], v[164:167], v[212:215], v[72:75]
	v_mfma_f32_16x16x32_bf16 v[116:119], v[168:171], v[184:187], v[116:119]
	v_mfma_f32_16x16x32_bf16 v[112:115], v[176:179], v[184:187], v[112:115]
	v_mfma_f32_16x16x32_bf16 v[100:103], v[168:171], v[192:195], v[100:103]
	v_mfma_f32_16x16x32_bf16 v[96:99], v[176:179], v[192:195], v[96:99]
	v_mfma_f32_16x16x32_bf16 v[84:87], v[168:171], v[200:203], v[84:87]
	v_mfma_f32_16x16x32_bf16 v[80:83], v[176:179], v[200:203], v[80:83]
	v_mfma_f32_16x16x32_bf16 v[68:71], v[168:171], v[208:211], v[68:71]
	v_mfma_f32_16x16x32_bf16 v[64:67], v[176:179], v[208:211], v[64:67]
	v_mfma_f32_16x16x32_bf16 v[116:119], v[172:175], v[188:191], v[116:119]
	v_mfma_f32_16x16x32_bf16 v[112:115], v[180:183], v[188:191], v[112:115]
	v_mfma_f32_16x16x32_bf16 v[100:103], v[172:175], v[196:199], v[100:103]
	v_mfma_f32_16x16x32_bf16 v[96:99], v[180:183], v[196:199], v[96:99]
	v_mfma_f32_16x16x32_bf16 v[84:87], v[172:175], v[204:207], v[84:87]
	v_mfma_f32_16x16x32_bf16 v[80:83], v[180:183], v[204:207], v[80:83]
	v_mfma_f32_16x16x32_bf16 v[68:71], v[172:175], v[212:215], v[68:71]
	v_mfma_f32_16x16x32_bf16 v[64:67], v[180:183], v[212:215], v[64:67]
	s_barrier
	s_setprio 1
	s_add_i32 s61, s52, s42
	s_mov_b32 m0, s61
	s_nop 0
	global_load_lds_dwordx4 v[216:217], off
	s_add_i32 m0, s61, 0x2000
	s_add_i32 s61, s53, s42
	global_load_lds_dwordx4 v[218:219], off
	s_mov_b32 m0, s61
	s_nop 0
	global_load_lds_dwordx4 v[246:247], off
	s_add_i32 m0, s61, 0x2000
	s_nop 0
	global_load_lds_dwordx4 v[248:249], off
	ds_read_b128 v[184:187], v157 offset:16384
	ds_read_b128 v[188:191], v157 offset:17408
	ds_read_b128 v[192:195], v157 offset:18432
	ds_read_b128 v[196:199], v157 offset:19456
	ds_read_b128 v[200:203], v157 offset:20480
	ds_read_b128 v[204:207], v157 offset:21504
	ds_read_b128 v[208:211], v157 offset:22528
	ds_read_b128 v[212:215], v157 offset:23552
	s_waitcnt vmcnt(4)
	s_waitcnt lgkmcnt(0)
	s_setprio 0
	s_barrier
; #define PG8_STAGE(bufoff, gbase, voff) do { _Pragma("unroll") for (int _i = 0; _i < 2; ++_i) \
;         __builtin_amdgcn_global_load_lds((const unsigned*)((const char*)(gbase) + (voff)[_i]), (PG8_LAS unsigned*)(lds + (bufoff) + ldsw + _i * 8192), 16, 0, 0); } while (0)
; #define PG8_LDA(dst, b, h) do { _Pragma("unroll") for (int m = 0; m < 4; ++m) _Pragma("unroll") for (int k = 0; k < 2; ++k) dst[m][k] = *(const PG8_LAS bf16x8*)(lds + PG8_SA(b, h) + aoff + m * 2048 + k * 1024); } while (0)
; #define PG8_LDB(dst, b, h) do { _Pragma("unroll") for (int n = 0; n < 2; ++n) _Pragma("unroll") for (int k = 0; k < 2; ++k) dst[n][k] = *(const PG8_LAS bf16x8*)(lds + PG8_SB(b, h) + boff + n * 2048 + k * 1024); } while (0)
; #define PG8_MMA(ai, bj, At, Bt) do { __builtin_amdgcn_s_setprio(1); _Pragma("unroll") for (int m = 0; m < 4; ++m) _Pragma("unroll") for (int n = 0; n < 2; ++n) _Pragma("unroll") for (int k = 0; k < 2; ++k) \
;         acc[ai][bj][m][n] = __builtin_amdgcn_mfma_f32_16x16x32_bf16(Bt[n][k], At[m][k], acc[ai][bj][m][n], 0, 0, 0); __builtin_amdgcn_s_setprio(0); } while (0)
; #define PG8_WAIT_V(n) asm volatile("s_waitcnt vmcnt(" #n ")" ::: "memory")
; #define PG8_WAIT_L(n) asm volatile("s_waitcnt lgkmcnt(" #n ")" ::: "memory")
; #define PG8_BAR __builtin_amdgcn_s_barrier()
; #define PG8_SCHED __builtin_amdgcn_sched_barrier(0)
; template <class Epi, class Sched, bool ALIGN_EPI = false, bool SP2 = false>
; __device__ __forceinline__ void gemm_phase(PG8_LAS unsigned char* lds, const Gemm g, const Sched& S, const Epi& E) {
;     ...
;             PG8_LDA(At, 0, 1); PG8_STAGE(PG8_SB(0, 0), b2, voffB); PG8_STAGE(PG8_SB(0, 1), b2 + hstep, voffB); PG8_STAGE(PG8_SA(0, 0), a2, voffA);
;             PG8_WAIT_V(8); PG8_WAIT_L(0); PG8_BAR; PG8_MMA(1, 0, At, B0); PG8_MMA(1, 1, At, B1); PG8_BAR; PG8_SCHED;
;             PG8_LDB(B0, 1, 0); PG8_LDB(B1, 1, 1); PG8_SCHED; PG8_LDA(At, 1, 0); PG8_STAGE(PG8_SA(0, 1), a2 + hstep, voffA);
;             PG8_WAIT_V(8); PG8_WAIT_L(0); PG8_BAR; PG8_MMA(0, 0, At, B0); PG8_MMA(0, 1, At, B1); PG8_BAR; PG8_SCHED;
	s_waitcnt lgkmcnt(0)
	v_mfma_f32_16x16x32_bf16 v[60:63], v[144:147], v[184:187], v[60:63]
	v_mfma_f32_16x16x32_bf16 v[56:59], v[160:163], v[184:187], v[56:59]
	v_mfma_f32_16x16x32_bf16 v[44:47], v[144:147], v[192:195], v[44:47]
	v_mfma_f32_16x16x32_bf16 v[40:43], v[160:163], v[192:195], v[40:43]
	v_mfma_f32_16x16x32_bf16 v[28:31], v[144:147], v[200:203], v[28:31]
	v_mfma_f32_16x16x32_bf16 v[24:27], v[160:163], v[200:203], v[24:27]
	v_mfma_f32_16x16x32_bf16 v[12:15], v[144:147], v[208:211], v[12:15]
	v_mfma_f32_16x16x32_bf16 v[8:11], v[160:163], v[208:211], v[8:11]
	v_mfma_f32_16x16x32_bf16 v[60:63], v[148:151], v[188:191], v[60:63]
	v_mfma_f32_16x16x32_bf16 v[56:59], v[164:167], v[188:191], v[56:59]
	v_mfma_f32_16x16x32_bf16 v[44:47], v[148:151], v[196:199], v[44:47]
	v_mfma_f32_16x16x32_bf16 v[40:43], v[164:167], v[196:199], v[40:43]
	v_mfma_f32_16x16x32_bf16 v[28:31], v[148:151], v[204:207], v[28:31]
	v_mfma_f32_16x16x32_bf16 v[24:27], v[164:167], v[204:207], v[24:27]
	v_mfma_f32_16x16x32_bf16 v[12:15], v[148:151], v[212:215], v[12:15]
	v_mfma_f32_16x16x32_bf16 v[8:11], v[164:167], v[212:215], v[8:11]
	v_mfma_f32_16x16x32_bf16 v[52:55], v[168:171], v[184:187], v[52:55]
	v_mfma_f32_16x16x32_bf16 v[48:51], v[176:179], v[184:187], v[48:51]
	v_mfma_f32_16x16x32_bf16 v[36:39], v[168:171], v[192:195], v[36:39]
	v_mfma_f32_16x16x32_bf16 v[32:35], v[176:179], v[192:195], v[32:35]
	v_mfma_f32_16x16x32_bf16 v[20:23], v[168:171], v[200:203], v[20:23]
	v_mfma_f32_16x16x32_bf16 v[16:19], v[176:179], v[200:203], v[16:19]
	v_mfma_f32_16x16x32_bf16 v[4:7], v[168:171], v[208:211], v[4:7]
	v_mfma_f32_16x16x32_bf16 v[0:3], v[176:179], v[208:211], v[0:3]
	v_mfma_f32_16x16x32_bf16 v[52:55], v[172:175], v[188:191], v[52:55]
	v_mfma_f32_16x16x32_bf16 v[48:51], v[180:183], v[188:191], v[48:51]
	v_mfma_f32_16x16x32_bf16 v[36:39], v[172:175], v[196:199], v[36:39]
	v_mfma_f32_16x16x32_bf16 v[32:35], v[180:183], v[196:199], v[32:35]
	v_mfma_f32_16x16x32_bf16 v[20:23], v[172:175], v[204:207], v[20:23]
	v_mfma_f32_16x16x32_bf16 v[16:19], v[180:183], v[204:207], v[16:19]
	v_mfma_f32_16x16x32_bf16 v[4:7], v[172:175], v[212:215], v[4:7]
	v_mfma_f32_16x16x32_bf16 v[0:3], v[180:183], v[212:215], v[0:3]
	s_barrier
	s_setprio 1
	s_add_i32 s61, 0, 0x18000
	s_add_i32 s62, 0, 0x1c000
	v_add_u32_e32 v164, s61, v153
	v_add_u32_e32 v180, s62, v153
	ds_read_b128 v[144:147], v164
	ds_read_b128 v[148:151], v164 offset:1024
	ds_read_b128 v[160:163], v164 offset:2048
	ds_read_b128 v[164:167], v164 offset:3072
	ds_read_b128 v[168:171], v180
	ds_read_b128 v[172:175], v180 offset:1024
	ds_read_b128 v[176:179], v180 offset:2048
	ds_read_b128 v[180:183], v180 offset:3072
	s_add_u32 s34, s34, 0x80000
	s_addc_u32 s35, s35, 0
	s_mov_b32 m0, s46
	v_lshl_add_u64 v[224:225], s[34:35], 0, v[134:135]
	ds_read_b128 v[184:187], v157 offset:32768
	ds_read_b128 v[188:191], v157 offset:33792
	ds_read_b128 v[192:195], v157 offset:34816
	ds_read_b128 v[196:199], v157 offset:35840
	ds_read_b128 v[200:203], v157 offset:36864
	ds_read_b128 v[204:207], v157 offset:37888
	ds_read_b128 v[208:211], v157 offset:38912
	ds_read_b128 v[212:215], v157 offset:39936
	global_load_lds_dwordx4 v[224:225], off
	v_lshl_add_u64 v[224:225], s[34:35], 0, v[130:131]
	s_mov_b32 m0, s47
	s_nop 0
	global_load_lds_dwordx4 v[224:225], off
	s_mov_b32 m0, s25
	s_nop 0
	global_load_lds_dwordx4 v[220:221], off
	s_mov_b32 m0, s45
	s_nop 0
	global_load_lds_dwordx4 v[222:223], off
	s_add_u32 s30, s30, 0x80080
	s_addc_u32 s31, s31, 0
	v_lshl_add_u64 v[216:217], v[216:217], 0, s[8:9]
	v_lshl_add_u64 v[218:219], v[218:219], 0, s[8:9]
	v_lshl_add_u64 v[246:247], s[30:31], 0, v[132:133]
	v_lshl_add_u64 v[248:249], s[30:31], 0, v[128:129]
	v_lshl_add_u64 v[250:251], v[220:221], 0, s[8:9]
	v_lshl_add_u64 v[252:253], v[222:223], 0, s[8:9]
	s_waitcnt vmcnt(10)
	s_waitcnt lgkmcnt(0)
	s_setprio 0
	s_barrier
; #define PG8_STAGE(bufoff, gbase, voff) do { _Pragma("unroll") for (int _i = 0; _i < 2; ++_i) \
;         __builtin_amdgcn_global_load_lds((const unsigned*)((const char*)(gbase) + (voff)[_i]), (PG8_LAS unsigned*)(lds + (bufoff) + ldsw + _i * 8192), 16, 0, 0); } while (0)
; #define PG8_LDA(dst, b, h) do { _Pragma("unroll") for (int m = 0; m < 4; ++m) _Pragma("unroll") for (int k = 0; k < 2; ++k) dst[m][k] = *(const PG8_LAS bf16x8*)(lds + PG8_SA(b, h) + aoff + m * 2048 + k * 1024); } while (0)
; #define PG8_MMA(ai, bj, At, Bt) do { __builtin_amdgcn_s_setprio(1); _Pragma("unroll") for (int m = 0; m < 4; ++m) _Pragma("unroll") for (int n = 0; n < 2; ++n) _Pragma("unroll") for (int k = 0; k < 2; ++k) \
;         acc[ai][bj][m][n] = __builtin_amdgcn_mfma_f32_16x16x32_bf16(Bt[n][k], At[m][k], acc[ai][bj][m][n], 0, 0, 0); __builtin_amdgcn_s_setprio(0); } while (0)
; #define PG8_WAIT_V(n) asm volatile("s_waitcnt vmcnt(" #n ")" ::: "memory")
; #define PG8_WAIT_L(n) asm volatile("s_waitcnt lgkmcnt(" #n ")" ::: "memory")
; #define PG8_BAR __builtin_amdgcn_s_barrier()
; #define PG8_SCHED __builtin_amdgcn_sched_barrier(0)
; template <class Epi, class Sched, bool ALIGN_EPI = false, bool SP2 = false>
; __device__ __forceinline__ void gemm_phase(PG8_LAS unsigned char* lds, const Gemm g, const Sched& S, const Epi& E) {
;     ...
;             PG8_WAIT_V(8); PG8_WAIT_L(0); PG8_BAR; PG8_MMA(0, 0, At, B0); PG8_MMA(0, 1, At, B1); PG8_BAR; PG8_SCHED;
;             PG8_LDA(At, 1, 1); PG8_STAGE(PG8_SB(1, 0), b3, voffB); PG8_STAGE(PG8_SB(1, 1), b3 + hstep, voffB); PG8_STAGE(PG8_SA(1, 0), a3, voffA);
;             PG8_WAIT_V(8); PG8_WAIT_L(0); PG8_BAR; PG8_MMA(1, 0, At, B0); PG8_MMA(1, 1, At, B1); PG8_BAR; PG8_SCHED;
;     ...
;         if constexpr (ALIGN_EPI) { if (wr == 0) PG8_BAR; }
	s_waitcnt lgkmcnt(0)
	v_mfma_f32_16x16x32_bf16 v[124:127], v[144:147], v[184:187], v[124:127]
	v_mfma_f32_16x16x32_bf16 v[120:123], v[160:163], v[184:187], v[120:123]
	v_mfma_f32_16x16x32_bf16 v[108:111], v[144:147], v[192:195], v[108:111]
	v_mfma_f32_16x16x32_bf16 v[104:107], v[160:163], v[192:195], v[104:107]
	v_mfma_f32_16x16x32_bf16 v[92:95], v[144:147], v[200:203], v[92:95]
	v_mfma_f32_16x16x32_bf16 v[88:91], v[160:163], v[200:203], v[88:91]
	v_mfma_f32_16x16x32_bf16 v[76:79], v[144:147], v[208:211], v[76:79]
	v_mfma_f32_16x16x32_bf16 v[72:75], v[160:163], v[208:211], v[72:75]
	v_mfma_f32_16x16x32_bf16 v[124:127], v[148:151], v[188:191], v[124:127]
	v_mfma_f32_16x16x32_bf16 v[120:123], v[164:167], v[188:191], v[120:123]
	v_mfma_f32_16x16x32_bf16 v[108:111], v[148:151], v[196:199], v[108:111]
	v_mfma_f32_16x16x32_bf16 v[104:107], v[164:167], v[196:199], v[104:107]
	v_mfma_f32_16x16x32_bf16 v[92:95], v[148:151], v[204:207], v[92:95]
	v_mfma_f32_16x16x32_bf16 v[88:91], v[164:167], v[204:207], v[88:91]
	v_mfma_f32_16x16x32_bf16 v[76:79], v[148:151], v[212:215], v[76:79]
	v_mfma_f32_16x16x32_bf16 v[72:75], v[164:167], v[212:215], v[72:75]
	v_mfma_f32_16x16x32_bf16 v[116:119], v[168:171], v[184:187], v[116:119]
	v_mfma_f32_16x16x32_bf16 v[112:115], v[176:179], v[184:187], v[112:115]
	v_mfma_f32_16x16x32_bf16 v[100:103], v[168:171], v[192:195], v[100:103]
	v_mfma_f32_16x16x32_bf16 v[96:99], v[176:179], v[192:195], v[96:99]
	v_mfma_f32_16x16x32_bf16 v[84:87], v[168:171], v[200:203], v[84:87]
	v_mfma_f32_16x16x32_bf16 v[80:83], v[176:179], v[200:203], v[80:83]
	v_mfma_f32_16x16x32_bf16 v[68:71], v[168:171], v[208:211], v[68:71]
	v_mfma_f32_16x16x32_bf16 v[64:67], v[176:179], v[208:211], v[64:67]
	v_mfma_f32_16x16x32_bf16 v[116:119], v[172:175], v[188:191], v[116:119]
	v_mfma_f32_16x16x32_bf16 v[112:115], v[180:183], v[188:191], v[112:115]
	v_mfma_f32_16x16x32_bf16 v[100:103], v[172:175], v[196:199], v[100:103]
	v_mfma_f32_16x16x32_bf16 v[96:99], v[180:183], v[196:199], v[96:99]
	v_mfma_f32_16x16x32_bf16 v[84:87], v[172:175], v[204:207], v[84:87]
	v_mfma_f32_16x16x32_bf16 v[80:83], v[180:183], v[204:207], v[80:83]
	v_mfma_f32_16x16x32_bf16 v[68:71], v[172:175], v[212:215], v[68:71]
	v_mfma_f32_16x16x32_bf16 v[64:67], v[180:183], v[212:215], v[64:67]
	s_barrier
	s_setprio 1
	s_add_i32 s34, s61, s42
	s_mov_b32 m0, s34
	s_nop 0
	global_load_lds_dwordx4 v[216:217], off
	s_add_i32 m0, s34, 0x2000
	s_add_i32 s34, s62, s42
	global_load_lds_dwordx4 v[218:219], off
	s_mov_b32 m0, s34
	s_nop 0
	global_load_lds_dwordx4 v[246:247], off
	s_add_i32 m0, s34, 0x2000
	s_nop 0
	global_load_lds_dwordx4 v[248:249], off
	ds_read_b128 v[184:187], v157 offset:49152
	ds_read_b128 v[188:191], v157 offset:50176
	ds_read_b128 v[192:195], v157 offset:51200
	ds_read_b128 v[196:199], v157 offset:52224
	ds_read_b128 v[200:203], v157 offset:53248
	ds_read_b128 v[204:207], v157 offset:54272
	ds_read_b128 v[208:211], v157 offset:55296
	ds_read_b128 v[212:215], v157 offset:56320
	s_waitcnt vmcnt(4)
	s_waitcnt lgkmcnt(0)
	s_setprio 0
	s_barrier
	s_waitcnt lgkmcnt(0)
	v_mfma_f32_16x16x32_bf16 v[60:63], v[144:147], v[184:187], v[60:63]
	v_mfma_f32_16x16x32_bf16 v[56:59], v[160:163], v[184:187], v[56:59]
	v_mfma_f32_16x16x32_bf16 v[44:47], v[144:147], v[192:195], v[44:47]
	v_mfma_f32_16x16x32_bf16 v[40:43], v[160:163], v[192:195], v[40:43]
	v_mfma_f32_16x16x32_bf16 v[28:31], v[144:147], v[200:203], v[28:31]
	v_mfma_f32_16x16x32_bf16 v[24:27], v[160:163], v[200:203], v[24:27]
	v_mfma_f32_16x16x32_bf16 v[12:15], v[144:147], v[208:211], v[12:15]
	v_mfma_f32_16x16x32_bf16 v[8:11], v[160:163], v[208:211], v[8:11]
	v_mfma_f32_16x16x32_bf16 v[60:63], v[148:151], v[188:191], v[60:63]
	v_mfma_f32_16x16x32_bf16 v[56:59], v[164:167], v[188:191], v[56:59]
	v_mfma_f32_16x16x32_bf16 v[44:47], v[148:151], v[196:199], v[44:47]
	v_mfma_f32_16x16x32_bf16 v[40:43], v[164:167], v[196:199], v[40:43]
	v_mfma_f32_16x16x32_bf16 v[28:31], v[148:151], v[204:207], v[28:31]
	v_mfma_f32_16x16x32_bf16 v[24:27], v[164:167], v[204:207], v[24:27]
	v_mfma_f32_16x16x32_bf16 v[12:15], v[148:151], v[212:215], v[12:15]
	v_mfma_f32_16x16x32_bf16 v[8:11], v[164:167], v[212:215], v[8:11]
	v_mfma_f32_16x16x32_bf16 v[52:55], v[168:171], v[184:187], v[52:55]
	v_mfma_f32_16x16x32_bf16 v[48:51], v[176:179], v[184:187], v[48:51]
	v_mfma_f32_16x16x32_bf16 v[36:39], v[168:171], v[192:195], v[36:39]
	v_mfma_f32_16x16x32_bf16 v[32:35], v[176:179], v[192:195], v[32:35]
	v_mfma_f32_16x16x32_bf16 v[20:23], v[168:171], v[200:203], v[20:23]
	v_mfma_f32_16x16x32_bf16 v[16:19], v[176:179], v[200:203], v[16:19]
	v_mfma_f32_16x16x32_bf16 v[4:7], v[168:171], v[208:211], v[4:7]
	v_mfma_f32_16x16x32_bf16 v[0:3], v[176:179], v[208:211], v[0:3]
	v_mfma_f32_16x16x32_bf16 v[52:55], v[172:175], v[188:191], v[52:55]
	v_mfma_f32_16x16x32_bf16 v[48:51], v[180:183], v[188:191], v[48:51]
	v_mfma_f32_16x16x32_bf16 v[36:39], v[172:175], v[196:199], v[36:39]
	v_mfma_f32_16x16x32_bf16 v[32:35], v[180:183], v[196:199], v[32:35]
	v_mfma_f32_16x16x32_bf16 v[20:23], v[172:175], v[204:207], v[20:23]
	v_mfma_f32_16x16x32_bf16 v[16:19], v[180:183], v[204:207], v[16:19]
	v_mfma_f32_16x16x32_bf16 v[4:7], v[172:175], v[212:215], v[4:7]
	v_mfma_f32_16x16x32_bf16 v[0:3], v[180:183], v[212:215], v[0:3]
	s_barrier
	s_add_i32 s60, s60, 2
	s_add_u32 s28, s28, 0x100
	s_addc_u32 s29, s29, 0
	s_add_u32 s58, s58, 0x100
	s_addc_u32 s59, s59, 0
	s_cmp_gt_u32 s60, 29
	s_cbranch_scc0 .LBB0_150
	s_and_b64 vcc, exec, s[10:11]
	s_cbranch_vccz .LBB0_153
	s_barrier

; #define PG8_STAGE(bufoff, gbase, voff) do { _Pragma("unroll") for (int _i = 0; _i < 2; ++_i) \
;         __builtin_amdgcn_global_load_lds((const unsigned*)((const char*)(gbase) + (voff)[_i]), (PG8_LAS unsigned*)(lds + (bufoff) + ldsw + _i * 8192), 16, 0, 0); } while (0)
; #define PG8_LDA(dst, b, h) do { _Pragma("unroll") for (int m = 0; m < 4; ++m) _Pragma("unroll") for (int k = 0; k < 2; ++k) dst[m][k] = *(const PG8_LAS bf16x8*)(lds + PG8_SA(b, h) + aoff + m * 2048 + k * 1024); } while (0)
; #define PG8_LDB(dst, b, h) do { _Pragma("unroll") for (int n = 0; n < 2; ++n) _Pragma("unroll") for (int k = 0; k < 2; ++k) dst[n][k] = *(const PG8_LAS bf16x8*)(lds + PG8_SB(b, h) + boff + n * 2048 + k * 1024); } while (0)
; #define PG8_WAIT_V(n) asm volatile("s_waitcnt vmcnt(" #n ")" ::: "memory")
; #define PG8_WAIT_L(n) asm volatile("s_waitcnt lgkmcnt(" #n ")" ::: "memory")
; #define PG8_BAR __builtin_amdgcn_s_barrier()
; #define PG8_SCHED __builtin_amdgcn_sched_barrier(0)
; template <class Epi, class Sched, bool ALIGN_EPI = false, bool SP2 = false>
; __device__ __forceinline__ void gemm_phase(PG8_LAS unsigned char* lds, const Gemm g, const Sched& S, const Epi& E) {
;     ...
;         const bool has_next = S.next(ui + 1, nxt);
;         const char* nA = has_next ? (const char*)g.A + (size_t)nxt.pm * tstep : cA; const char* nB = has_next ? (const char*)g.Bt + (size_t)nxt.pn * tstep : cB;
;         for (int t = 0; t < nt; t += 2) {
;             const bool last = (t == nt - 2);
;             const char* a1 = cA + (size_t)(t + 1) * kstep;
;             const char* a2 = last ? nA : cA + (size_t)(t + 2) * kstep; const char* b2 = last ? nB : cB + (size_t)(t + 2) * kstep;
;             const char* a3 = a2 + kstep; const char* b3 = b2 + kstep;
;             if (last && has_next) S.a_ready(nxt);
;             if constexpr (SP2) {
;             PG8_LDB(B0, 0, 0); PG8_LDB(B1, 0, 1); PG8_SCHED; PG8_LDA(At, 0, 0); PG8_STAGE(PG8_SA(1, 1), a1 + hstep, voffA);
;             PG8_WAIT_V(8); PG8_WAIT_L(0); PG8_BAR; PG8_MMA(0, 0, At, B0); PG8_MMA(0, 1, At, B1); PG8_BAR; PG8_SCHED;
;             PG8_LDA(At, 0, 1); PG8_STAGE(PG8_SB(0, 0), b2, voffB); PG8_STAGE(PG8_SB(0, 1), b2 + hstep, voffB); PG8_STAGE(PG8_SA(0, 0), a2, voffA);
;             PG8_WAIT_V(8); PG8_WAIT_L(0); PG8_BAR; PG8_MMA(1, 0, At, B0); PG8_MMA(1, 1, At, B1); PG8_BAR; PG8_SCHED;
.LBB0_621:
	s_setprio 1
	ds_read_b128 v[128:131], v189
	ds_read_b128 v[132:135], v189 offset:1024
	ds_read_b128 v[136:139], v189 offset:2048
	ds_read_b128 v[140:143], v189 offset:3072
	ds_read_b128 v[144:147], v190
	ds_read_b128 v[148:151], v190 offset:1024
	ds_read_b128 v[168:171], v190 offset:2048
	ds_read_b128 v[172:175], v190 offset:3072
	s_add_u32 s36, s34, 0xfff80080
	s_addc_u32 s37, s35, -1
	s_cmp_eq_u32 s60, 28
	s_cselect_b32 s39, s17, s37
	s_cselect_b32 s38, s29, s36
	s_cselect_b32 s37, s15, s59
	s_cselect_b32 s36, s57, s58
	v_lshl_add_u64 v[184:185], s[34:35], 0, v[160:161]
	s_add_i32 m0, s31, 0xc000
	ds_read_b128 v[176:179], v191
	ds_read_b128 v[180:183], v191 offset:1024
	ds_read_b128 v[192:195], v191 offset:2048
	ds_read_b128 v[196:199], v191 offset:3072
	ds_read_b128 v[200:203], v191 offset:4096
	ds_read_b128 v[204:207], v191 offset:5120
	ds_read_b128 v[208:211], v191 offset:6144
	ds_read_b128 v[212:215], v191 offset:7168
	global_load_lds_dwordx4 v[184:185], off
	v_lshl_add_u64 v[184:185], s[34:35], 0, v[162:163]
	s_add_i32 m0, s31, 0xe000
	s_nop 0
	global_load_lds_dwordx4 v[184:185], off
	s_mov_b32 m0, s50
	s_nop 0
	global_load_lds_dwordx4 v[250:251], off
	s_mov_b32 m0, s51
	s_nop 0
	global_load_lds_dwordx4 v[252:253], off
	s_add_u32 s62, s36, 0x80000
	s_addc_u32 s63, s37, 0
	v_lshl_add_u64 v[184:185], s[36:37], 0, v[154:155]
	v_lshl_add_u64 v[216:217], s[36:37], 0, v[158:159]
	v_lshl_add_u64 v[246:247], s[62:63], 0, v[154:155]
	v_lshl_add_u64 v[220:221], s[38:39], 0, v[156:157]
	v_lshl_add_u64 v[248:249], s[62:63], 0, v[158:159]
	v_lshl_add_u64 v[218:219], s[38:39], 0, v[152:153]
	s_waitcnt vmcnt(10)
	s_waitcnt lgkmcnt(0)
	s_setprio 0
	s_barrier
	s_waitcnt lgkmcnt(0)
	v_mfma_f32_16x16x32_bf16 v[124:127], v[128:131], v[176:179], v[124:127]
	v_mfma_f32_16x16x32_bf16 v[120:123], v[136:139], v[176:179], v[120:123]
	v_mfma_f32_16x16x32_bf16 v[108:111], v[128:131], v[192:195], v[108:111]
	v_mfma_f32_16x16x32_bf16 v[104:107], v[136:139], v[192:195], v[104:107]
	v_mfma_f32_16x16x32_bf16 v[92:95], v[128:131], v[200:203], v[92:95]
	v_mfma_f32_16x16x32_bf16 v[88:91], v[136:139], v[200:203], v[88:91]
	v_mfma_f32_16x16x32_bf16 v[76:79], v[128:131], v[208:211], v[76:79]
	v_mfma_f32_16x16x32_bf16 v[72:75], v[136:139], v[208:211], v[72:75]
	v_mfma_f32_16x16x32_bf16 v[124:127], v[132:135], v[180:183], v[124:127]
	v_mfma_f32_16x16x32_bf16 v[120:123], v[140:143], v[180:183], v[120:123]
	v_mfma_f32_16x16x32_bf16 v[108:111], v[132:135], v[196:199], v[108:111]
	v_mfma_f32_16x16x32_bf16 v[104:107], v[140:143], v[196:199], v[104:107]
	v_mfma_f32_16x16x32_bf16 v[92:95], v[132:135], v[204:207], v[92:95]
	v_mfma_f32_16x16x32_bf16 v[88:91], v[140:143], v[204:207], v[88:91]
	v_mfma_f32_16x16x32_bf16 v[76:79], v[132:135], v[212:215], v[76:79]
	v_mfma_f32_16x16x32_bf16 v[72:75], v[140:143], v[212:215], v[72:75]
	v_mfma_f32_16x16x32_bf16 v[116:119], v[144:147], v[176:179], v[116:119]
	v_mfma_f32_16x16x32_bf16 v[112:115], v[168:171], v[176:179], v[112:115]
	v_mfma_f32_16x16x32_bf16 v[100:103], v[144:147], v[192:195], v[100:103]
	v_mfma_f32_16x16x32_bf16 v[96:99], v[168:171], v[192:195], v[96:99]
	v_mfma_f32_16x16x32_bf16 v[84:87], v[144:147], v[200:203], v[84:87]
	v_mfma_f32_16x16x32_bf16 v[80:83], v[168:171], v[200:203], v[80:83]
	v_mfma_f32_16x16x32_bf16 v[68:71], v[144:147], v[208:211], v[68:71]
	v_mfma_f32_16x16x32_bf16 v[64:67], v[168:171], v[208:211], v[64:67]
	v_mfma_f32_16x16x32_bf16 v[116:119], v[148:151], v[180:183], v[116:119]
	v_mfma_f32_16x16x32_bf16 v[112:115], v[172:175], v[180:183], v[112:115]
	v_mfma_f32_16x16x32_bf16 v[100:103], v[148:151], v[196:199], v[100:103]
	v_mfma_f32_16x16x32_bf16 v[96:99], v[172:175], v[196:199], v[96:99]
	v_mfma_f32_16x16x32_bf16 v[84:87], v[148:151], v[204:207], v[84:87]
	v_mfma_f32_16x16x32_bf16 v[80:83], v[172:175], v[204:207], v[80:83]
	v_mfma_f32_16x16x32_bf16 v[68:71], v[148:151], v[212:215], v[68:71]
	v_mfma_f32_16x16x32_bf16 v[64:67], v[172:175], v[212:215], v[64:67]
	s_barrier
	s_setprio 1
	s_add_i32 s61, s54, s45
	s_mov_b32 m0, s61
	s_nop 0
	global_load_lds_dwordx4 v[184:185], off
	s_add_i32 m0, s61, 0x2000
	s_add_i32 s61, s55, s45
	global_load_lds_dwordx4 v[216:217], off
	s_mov_b32 m0, s61
	s_nop 0
	global_load_lds_dwordx4 v[246:247], off
	s_add_i32 m0, s61, 0x2000
	s_nop 0
	global_load_lds_dwordx4 v[248:249], off
	ds_read_b128 v[176:179], v191 offset:16384
	ds_read_b128 v[180:183], v191 offset:17408
	ds_read_b128 v[192:195], v191 offset:18432
	ds_read_b128 v[196:199], v191 offset:19456
	ds_read_b128 v[200:203], v191 offset:20480
	ds_read_b128 v[204:207], v191 offset:21504
	ds_read_b128 v[208:211], v191 offset:22528
	ds_read_b128 v[212:215], v191 offset:23552
	s_waitcnt vmcnt(4)
	s_waitcnt lgkmcnt(0)
	s_setprio 0
	s_barrier
; #define PG8_STAGE(bufoff, gbase, voff) do { _Pragma("unroll") for (int _i = 0; _i < 2; ++_i) \
;         __builtin_amdgcn_global_load_lds((const unsigned*)((const char*)(gbase) + (voff)[_i]), (PG8_LAS unsigned*)(lds + (bufoff) + ldsw + _i * 8192), 16, 0, 0); } while (0)
; #define PG8_LDA(dst, b, h) do { _Pragma("unroll") for (int m = 0; m < 4; ++m) _Pragma("unroll") for (int k = 0; k < 2; ++k) dst[m][k] = *(const PG8_LAS bf16x8*)(lds + PG8_SA(b, h) + aoff + m * 2048 + k * 1024); } while (0)
; #define PG8_LDB(dst, b, h) do { _Pragma("unroll") for (int n = 0; n < 2; ++n) _Pragma("unroll") for (int k = 0; k < 2; ++k) dst[n][k] = *(const PG8_LAS bf16x8*)(lds + PG8_SB(b, h) + boff + n * 2048 + k * 1024); } while (0)
; #define PG8_MMA(ai, bj, At, Bt) do { __builtin_amdgcn_s_setprio(1); _Pragma("unroll") for (int m = 0; m < 4; ++m) _Pragma("unroll") for (int n = 0; n < 2; ++n) _Pragma("unroll") for (int k = 0; k < 2; ++k) \
;         acc[ai][bj][m][n] = __builtin_amdgcn_mfma_f32_16x16x32_bf16(Bt[n][k], At[m][k], acc[ai][bj][m][n], 0, 0, 0); __builtin_amdgcn_s_setprio(0); } while (0)
; #define PG8_WAIT_V(n) asm volatile("s_waitcnt vmcnt(" #n ")" ::: "memory")
; #define PG8_WAIT_L(n) asm volatile("s_waitcnt lgkmcnt(" #n ")" ::: "memory")
; #define PG8_BAR __builtin_amdgcn_s_barrier()
; #define PG8_SCHED __builtin_amdgcn_sched_barrier(0)
; template <class Epi, class Sched, bool ALIGN_EPI = false, bool SP2 = false>
; __device__ __forceinline__ void gemm_phase(PG8_LAS unsigned char* lds, const Gemm g, const Sched& S, const Epi& E) {
;     ...
;             PG8_LDA(At, 0, 1); PG8_STAGE(PG8_SB(0, 0), b2, voffB); PG8_STAGE(PG8_SB(0, 1), b2 + hstep, voffB); PG8_STAGE(PG8_SA(0, 0), a2, voffA);
;             PG8_WAIT_V(8); PG8_WAIT_L(0); PG8_BAR; PG8_MMA(1, 0, At, B0); PG8_MMA(1, 1, At, B1); PG8_BAR; PG8_SCHED;
;             PG8_LDB(B0, 1, 0); PG8_LDB(B1, 1, 1); PG8_SCHED; PG8_LDA(At, 1, 0); PG8_STAGE(PG8_SA(0, 1), a2 + hstep, voffA);
;             PG8_WAIT_V(8); PG8_WAIT_L(0); PG8_BAR; PG8_MMA(0, 0, At, B0); PG8_MMA(0, 1, At, B1); PG8_BAR; PG8_SCHED;
	s_waitcnt lgkmcnt(0)
	v_mfma_f32_16x16x32_bf16 v[60:63], v[128:131], v[176:179], v[60:63]
	v_mfma_f32_16x16x32_bf16 v[56:59], v[136:139], v[176:179], v[56:59]
	v_mfma_f32_16x16x32_bf16 v[44:47], v[128:131], v[192:195], v[44:47]
	v_mfma_f32_16x16x32_bf16 v[40:43], v[136:139], v[192:195], v[40:43]
	v_mfma_f32_16x16x32_bf16 v[28:31], v[128:131], v[200:203], v[28:31]
	v_mfma_f32_16x16x32_bf16 v[24:27], v[136:139], v[200:203], v[24:27]
	v_mfma_f32_16x16x32_bf16 v[12:15], v[128:131], v[208:211], v[12:15]
	v_mfma_f32_16x16x32_bf16 v[8:11], v[136:139], v[208:211], v[8:11]
	v_mfma_f32_16x16x32_bf16 v[60:63], v[132:135], v[180:183], v[60:63]
	v_mfma_f32_16x16x32_bf16 v[56:59], v[140:143], v[180:183], v[56:59]
	v_mfma_f32_16x16x32_bf16 v[44:47], v[132:135], v[196:199], v[44:47]
	v_mfma_f32_16x16x32_bf16 v[40:43], v[140:143], v[196:199], v[40:43]
	v_mfma_f32_16x16x32_bf16 v[28:31], v[132:135], v[204:207], v[28:31]
	v_mfma_f32_16x16x32_bf16 v[24:27], v[140:143], v[204:207], v[24:27]
	v_mfma_f32_16x16x32_bf16 v[12:15], v[132:135], v[212:215], v[12:15]
	v_mfma_f32_16x16x32_bf16 v[8:11], v[140:143], v[212:215], v[8:11]
	v_mfma_f32_16x16x32_bf16 v[52:55], v[144:147], v[176:179], v[52:55]
	v_mfma_f32_16x16x32_bf16 v[48:51], v[168:171], v[176:179], v[48:51]
	v_mfma_f32_16x16x32_bf16 v[36:39], v[144:147], v[192:195], v[36:39]
	v_mfma_f32_16x16x32_bf16 v[32:35], v[168:171], v[192:195], v[32:35]
	v_mfma_f32_16x16x32_bf16 v[20:23], v[144:147], v[200:203], v[20:23]
	v_mfma_f32_16x16x32_bf16 v[16:19], v[168:171], v[200:203], v[16:19]
	v_mfma_f32_16x16x32_bf16 v[4:7], v[144:147], v[208:211], v[4:7]
	v_mfma_f32_16x16x32_bf16 v[0:3], v[168:171], v[208:211], v[0:3]
	v_mfma_f32_16x16x32_bf16 v[52:55], v[148:151], v[180:183], v[52:55]
	v_mfma_f32_16x16x32_bf16 v[48:51], v[172:175], v[180:183], v[48:51]
	v_mfma_f32_16x16x32_bf16 v[36:39], v[148:151], v[196:199], v[36:39]
	v_mfma_f32_16x16x32_bf16 v[32:35], v[172:175], v[196:199], v[32:35]
	v_mfma_f32_16x16x32_bf16 v[20:23], v[148:151], v[204:207], v[20:23]
	v_mfma_f32_16x16x32_bf16 v[16:19], v[172:175], v[204:207], v[16:19]
	v_mfma_f32_16x16x32_bf16 v[4:7], v[148:151], v[212:215], v[4:7]
	v_mfma_f32_16x16x32_bf16 v[0:3], v[172:175], v[212:215], v[0:3]
	s_barrier
	s_setprio 1
	s_add_i32 s61, 0, 0x18000
	s_add_i32 s62, 0, 0x1c000
	v_add_u32_e32 v140, s61, v187
	v_add_u32_e32 v172, s62, v187
	ds_read_b128 v[128:131], v140
	ds_read_b128 v[132:135], v140 offset:1024
	ds_read_b128 v[136:139], v140 offset:2048
	ds_read_b128 v[140:143], v140 offset:3072
	ds_read_b128 v[144:147], v172
	ds_read_b128 v[148:151], v172 offset:1024
	ds_read_b128 v[168:171], v172 offset:2048
	ds_read_b128 v[172:175], v172 offset:3072
	s_add_u32 s38, s38, 0x80000
	s_addc_u32 s39, s39, 0
	s_mov_b32 m0, s47
	v_lshl_add_u64 v[222:223], s[38:39], 0, v[152:153]
	ds_read_b128 v[176:179], v191 offset:32768
	ds_read_b128 v[180:183], v191 offset:33792
	ds_read_b128 v[192:195], v191 offset:34816
	ds_read_b128 v[196:199], v191 offset:35840
	ds_read_b128 v[200:203], v191 offset:36864
	ds_read_b128 v[204:207], v191 offset:37888
	ds_read_b128 v[208:211], v191 offset:38912
	ds_read_b128 v[212:215], v191 offset:39936
	global_load_lds_dwordx4 v[222:223], off
	v_lshl_add_u64 v[222:223], s[38:39], 0, v[156:157]
	s_mov_b32 m0, s48
	s_nop 0
	global_load_lds_dwordx4 v[222:223], off
	s_mov_b32 m0, s31
	s_nop 0
	global_load_lds_dwordx4 v[218:219], off
	s_mov_b32 m0, s46
	s_nop 0
	global_load_lds_dwordx4 v[220:221], off
	s_add_u32 s36, s36, 0x80080
	s_addc_u32 s37, s37, 0
	v_lshl_add_u64 v[184:185], v[184:185], 0, s[10:11]
	v_lshl_add_u64 v[216:217], v[216:217], 0, s[10:11]
	v_lshl_add_u64 v[246:247], s[36:37], 0, v[154:155]
	v_lshl_add_u64 v[248:249], s[36:37], 0, v[158:159]
	v_lshl_add_u64 v[250:251], v[218:219], 0, s[10:11]
	v_lshl_add_u64 v[252:253], v[220:221], 0, s[10:11]
	s_waitcnt vmcnt(10)
	s_waitcnt lgkmcnt(0)
	s_setprio 0
	s_barrier
; #define PG8_STAGE(bufoff, gbase, voff) do { _Pragma("unroll") for (int _i = 0; _i < 2; ++_i) \
;         __builtin_amdgcn_global_load_lds((const unsigned*)((const char*)(gbase) + (voff)[_i]), (PG8_LAS unsigned*)(lds + (bufoff) + ldsw + _i * 8192), 16, 0, 0); } while (0)
; #define PG8_LDA(dst, b, h) do { _Pragma("unroll") for (int m = 0; m < 4; ++m) _Pragma("unroll") for (int k = 0; k < 2; ++k) dst[m][k] = *(const PG8_LAS bf16x8*)(lds + PG8_SA(b, h) + aoff + m * 2048 + k * 1024); } while (0)
; #define PG8_MMA(ai, bj, At, Bt) do { __builtin_amdgcn_s_setprio(1); _Pragma("unroll") for (int m = 0; m < 4; ++m) _Pragma("unroll") for (int n = 0; n < 2; ++n) _Pragma("unroll") for (int k = 0; k < 2; ++k) \
;         acc[ai][bj][m][n] = __builtin_amdgcn_mfma_f32_16x16x32_bf16(Bt[n][k], At[m][k], acc[ai][bj][m][n], 0, 0, 0); __builtin_amdgcn_s_setprio(0); } while (0)
; #define PG8_WAIT_V(n) asm volatile("s_waitcnt vmcnt(" #n ")" ::: "memory")
; #define PG8_WAIT_L(n) asm volatile("s_waitcnt lgkmcnt(" #n ")" ::: "memory")
; #define PG8_BAR __builtin_amdgcn_s_barrier()
; #define PG8_SCHED __builtin_amdgcn_sched_barrier(0)
; template <class Epi, class Sched, bool ALIGN_EPI = false, bool SP2 = false>
; __device__ __forceinline__ void gemm_phase(PG8_LAS unsigned char* lds, const Gemm g, const Sched& S, const Epi& E) {
;     ...
;             PG8_WAIT_V(8); PG8_WAIT_L(0); PG8_BAR; PG8_MMA(0, 0, At, B0); PG8_MMA(0, 1, At, B1); PG8_BAR; PG8_SCHED;
;             PG8_LDA(At, 1, 1); PG8_STAGE(PG8_SB(1, 0), b3, voffB); PG8_STAGE(PG8_SB(1, 1), b3 + hstep, voffB); PG8_STAGE(PG8_SA(1, 0), a3, voffA);
;             PG8_WAIT_V(8); PG8_WAIT_L(0); PG8_BAR; PG8_MMA(1, 0, At, B0); PG8_MMA(1, 1, At, B1); PG8_BAR; PG8_SCHED;
	s_waitcnt lgkmcnt(0)
	v_mfma_f32_16x16x32_bf16 v[124:127], v[128:131], v[176:179], v[124:127]
	v_mfma_f32_16x16x32_bf16 v[120:123], v[136:139], v[176:179], v[120:123]
	v_mfma_f32_16x16x32_bf16 v[108:111], v[128:131], v[192:195], v[108:111]
	v_mfma_f32_16x16x32_bf16 v[104:107], v[136:139], v[192:195], v[104:107]
	v_mfma_f32_16x16x32_bf16 v[92:95], v[128:131], v[200:203], v[92:95]
	v_mfma_f32_16x16x32_bf16 v[88:91], v[136:139], v[200:203], v[88:91]
	v_mfma_f32_16x16x32_bf16 v[76:79], v[128:131], v[208:211], v[76:79]
	v_mfma_f32_16x16x32_bf16 v[72:75], v[136:139], v[208:211], v[72:75]
	v_mfma_f32_16x16x32_bf16 v[124:127], v[132:135], v[180:183], v[124:127]
	v_mfma_f32_16x16x32_bf16 v[120:123], v[140:143], v[180:183], v[120:123]
	v_mfma_f32_16x16x32_bf16 v[108:111], v[132:135], v[196:199], v[108:111]
	v_mfma_f32_16x16x32_bf16 v[104:107], v[140:143], v[196:199], v[104:107]
	v_mfma_f32_16x16x32_bf16 v[92:95], v[132:135], v[204:207], v[92:95]
	v_mfma_f32_16x16x32_bf16 v[88:91], v[140:143], v[204:207], v[88:91]
	v_mfma_f32_16x16x32_bf16 v[76:79], v[132:135], v[212:215], v[76:79]
	v_mfma_f32_16x16x32_bf16 v[72:75], v[140:143], v[212:215], v[72:75]
	v_mfma_f32_16x16x32_bf16 v[116:119], v[144:147], v[176:179], v[116:119]
	v_mfma_f32_16x16x32_bf16 v[112:115], v[168:171], v[176:179], v[112:115]
	v_mfma_f32_16x16x32_bf16 v[100:103], v[144:147], v[192:195], v[100:103]
	v_mfma_f32_16x16x32_bf16 v[96:99], v[168:171], v[192:195], v[96:99]
	v_mfma_f32_16x16x32_bf16 v[84:87], v[144:147], v[200:203], v[84:87]
	v_mfma_f32_16x16x32_bf16 v[80:83], v[168:171], v[200:203], v[80:83]
	v_mfma_f32_16x16x32_bf16 v[68:71], v[144:147], v[208:211], v[68:71]
	v_mfma_f32_16x16x32_bf16 v[64:67], v[168:171], v[208:211], v[64:67]
	v_mfma_f32_16x16x32_bf16 v[116:119], v[148:151], v[180:183], v[116:119]
	v_mfma_f32_16x16x32_bf16 v[112:115], v[172:175], v[180:183], v[112:115]
	v_mfma_f32_16x16x32_bf16 v[100:103], v[148:151], v[196:199], v[100:103]
	v_mfma_f32_16x16x32_bf16 v[96:99], v[172:175], v[196:199], v[96:99]
	v_mfma_f32_16x16x32_bf16 v[84:87], v[148:151], v[204:207], v[84:87]
	v_mfma_f32_16x16x32_bf16 v[80:83], v[172:175], v[204:207], v[80:83]
	v_mfma_f32_16x16x32_bf16 v[68:71], v[148:151], v[212:215], v[68:71]
	v_mfma_f32_16x16x32_bf16 v[64:67], v[172:175], v[212:215], v[64:67]
	s_barrier
	s_setprio 1
	s_add_i32 s38, s61, s45
	s_mov_b32 m0, s38
	s_nop 0
	global_load_lds_dwordx4 v[184:185], off
	s_add_i32 m0, s38, 0x2000
	s_add_i32 s38, s62, s45
	global_load_lds_dwordx4 v[216:217], off
	s_mov_b32 m0, s38
	s_nop 0
	global_load_lds_dwordx4 v[246:247], off
	s_add_i32 m0, s38, 0x2000
	s_nop 0
	global_load_lds_dwordx4 v[248:249], off
	ds_read_b128 v[176:179], v191 offset:49152
	ds_read_b128 v[180:183], v191 offset:50176
	ds_read_b128 v[192:195], v191 offset:51200
	ds_read_b128 v[196:199], v191 offset:52224
	ds_read_b128 v[200:203], v191 offset:53248
	ds_read_b128 v[204:207], v191 offset:54272
	ds_read_b128 v[208:211], v191 offset:55296
	ds_read_b128 v[212:215], v191 offset:56320
	s_waitcnt vmcnt(4)
	s_waitcnt lgkmcnt(0)
	s_setprio 0
	s_barrier
	s_waitcnt lgkmcnt(0)
	v_mfma_f32_16x16x32_bf16 v[60:63], v[128:131], v[176:179], v[60:63]
	v_mfma_f32_16x16x32_bf16 v[56:59], v[136:139], v[176:179], v[56:59]
	v_mfma_f32_16x16x32_bf16 v[44:47], v[128:131], v[192:195], v[44:47]
	v_mfma_f32_16x16x32_bf16 v[40:43], v[136:139], v[192:195], v[40:43]
	v_mfma_f32_16x16x32_bf16 v[28:31], v[128:131], v[200:203], v[28:31]
	v_mfma_f32_16x16x32_bf16 v[24:27], v[136:139], v[200:203], v[24:27]
	v_mfma_f32_16x16x32_bf16 v[12:15], v[128:131], v[208:211], v[12:15]
	v_mfma_f32_16x16x32_bf16 v[8:11], v[136:139], v[208:211], v[8:11]
	v_mfma_f32_16x16x32_bf16 v[60:63], v[132:135], v[180:183], v[60:63]
	v_mfma_f32_16x16x32_bf16 v[56:59], v[140:143], v[180:183], v[56:59]
	v_mfma_f32_16x16x32_bf16 v[44:47], v[132:135], v[196:199], v[44:47]
	v_mfma_f32_16x16x32_bf16 v[40:43], v[140:143], v[196:199], v[40:43]
	v_mfma_f32_16x16x32_bf16 v[28:31], v[132:135], v[204:207], v[28:31]
	v_mfma_f32_16x16x32_bf16 v[24:27], v[140:143], v[204:207], v[24:27]
	v_mfma_f32_16x16x32_bf16 v[12:15], v[132:135], v[212:215], v[12:15]
	v_mfma_f32_16x16x32_bf16 v[8:11], v[140:143], v[212:215], v[8:11]
	v_mfma_f32_16x16x32_bf16 v[52:55], v[144:147], v[176:179], v[52:55]
	v_mfma_f32_16x16x32_bf16 v[48:51], v[168:171], v[176:179], v[48:51]
	v_mfma_f32_16x16x32_bf16 v[36:39], v[144:147], v[192:195], v[36:39]
	v_mfma_f32_16x16x32_bf16 v[32:35], v[168:171], v[192:195], v[32:35]
	v_mfma_f32_16x16x32_bf16 v[20:23], v[144:147], v[200:203], v[20:23]
	v_mfma_f32_16x16x32_bf16 v[16:19], v[168:171], v[200:203], v[16:19]
	v_mfma_f32_16x16x32_bf16 v[4:7], v[144:147], v[208:211], v[4:7]
	v_mfma_f32_16x16x32_bf16 v[0:3], v[168:171], v[208:211], v[0:3]
	v_mfma_f32_16x16x32_bf16 v[52:55], v[148:151], v[180:183], v[52:55]
	v_mfma_f32_16x16x32_bf16 v[48:51], v[172:175], v[180:183], v[48:51]
	v_mfma_f32_16x16x32_bf16 v[36:39], v[148:151], v[196:199], v[36:39]
	v_mfma_f32_16x16x32_bf16 v[32:35], v[172:175], v[196:199], v[32:35]
	v_mfma_f32_16x16x32_bf16 v[20:23], v[148:151], v[204:207], v[20:23]
	v_mfma_f32_16x16x32_bf16 v[16:19], v[172:175], v[204:207], v[16:19]
	v_mfma_f32_16x16x32_bf16 v[4:7], v[148:151], v[212:215], v[4:7]
	v_mfma_f32_16x16x32_bf16 v[0:3], v[172:175], v[212:215], v[0:3]
	s_barrier
	s_add_i32 s60, s60, 2
	s_add_u32 s34, s34, 0x100
	s_addc_u32 s35, s35, 0
	s_add_u32 s58, s58, 0x100
	s_addc_u32 s59, s59, 0
	s_cmp_gt_u32 s60, 29
	s_cbranch_scc0 .LBB0_621
	s_and_b64 vcc, exec, s[12:13]
	s_cbranch_vccz .LBB0_624
	s_barrier

; #define PG8_STAGE(bufoff, gbase, voff) do { _Pragma("unroll") for (int _i = 0; _i < 2; ++_i) \
;         __builtin_amdgcn_global_load_lds((const unsigned*)((const char*)(gbase) + (voff)[_i]), (PG8_LAS unsigned*)(lds + (bufoff) + ldsw + _i * 8192), 16, 0, 0); } while (0)
; #define PG8_LDA(dst, b, h) do { _Pragma("unroll") for (int m = 0; m < 4; ++m) _Pragma("unroll") for (int k = 0; k < 2; ++k) dst[m][k] = *(const PG8_LAS bf16x8*)(lds + PG8_SA(b, h) + aoff + m * 2048 + k * 1024); } while (0)
; #define PG8_LDB(dst, b, h) do { _Pragma("unroll") for (int n = 0; n < 2; ++n) _Pragma("unroll") for (int k = 0; k < 2; ++k) dst[n][k] = *(const PG8_LAS bf16x8*)(lds + PG8_SB(b, h) + boff + n * 2048 + k * 1024); } while (0)
; #define PG8_MMA(ai, bj, At, Bt) do { __builtin_amdgcn_s_setprio(1); _Pragma("unroll") for (int m = 0; m < 4; ++m) _Pragma("unroll") for (int n = 0; n < 2; ++n) _Pragma("unroll") for (int k = 0; k < 2; ++k) \
;         acc[ai][bj][m][n] = __builtin_amdgcn_mfma_f32_16x16x32_bf16(Bt[n][k], At[m][k], acc[ai][bj][m][n], 0, 0, 0); __builtin_amdgcn_s_setprio(0); } while (0)
; #define PG8_WAIT_V(n) asm volatile("s_waitcnt vmcnt(" #n ")" ::: "memory")
; #define PG8_WAIT_L(n) asm volatile("s_waitcnt lgkmcnt(" #n ")" ::: "memory")
; template <class Epi, class Sched, bool ALIGN_EPI = false, bool SP2 = false>
; __device__ __forceinline__ void gemm_phase(PG8_LAS unsigned char* lds, const Gemm g, const Sched& S, const Epi& E) {
;     ...
;             const bool last = (t == nt - 2);
;             const char* a1 = cA + (size_t)(t + 1) * kstep;
;             const char* a2 = last ? nA : cA + (size_t)(t + 2) * kstep; const char* b2 = last ? nB : cB + (size_t)(t + 2) * kstep;
;             const char* a3 = a2 + kstep; const char* b3 = b2 + kstep;
;             if (last && has_next) S.a_ready(nxt);
;             if constexpr (SP2) {
;             PG8_LDB(B0, 0, 0); PG8_LDB(B1, 0, 1); PG8_SCHED; PG8_LDA(At, 0, 0); PG8_STAGE(PG8_SA(1, 1), a1 + hstep, voffA);
;             PG8_WAIT_V(8); PG8_WAIT_L(0); PG8_BAR; PG8_MMA(0, 0, At, B0); PG8_MMA(0, 1, At, B1); PG8_BAR; PG8_SCHED;
;             PG8_LDA(At, 0, 1); PG8_STAGE(PG8_SB(0, 0), b2, voffB); PG8_STAGE(PG8_SB(0, 1), b2 + hstep, voffB); PG8_STAGE(PG8_SA(0, 0), a2, voffA);
;             PG8_WAIT_V(8); PG8_WAIT_L(0); PG8_BAR; PG8_MMA(1, 0, At, B0); PG8_MMA(1, 1, At, B1); PG8_BAR; PG8_SCHED;
.LBB0_705:
	s_setprio 1
	ds_read_b128 v[144:147], v151
	ds_read_b128 v[156:159], v151 offset:1024
	ds_read_b128 v[160:163], v151 offset:2048
	ds_read_b128 v[164:167], v151 offset:3072
	ds_read_b128 v[168:171], v152
	ds_read_b128 v[172:175], v152 offset:1024
	ds_read_b128 v[176:179], v152 offset:2048
	ds_read_b128 v[180:183], v152 offset:3072
	s_add_u32 s30, s28, 0xfff80080
	s_addc_u32 s31, s29, -1
	s_cmp_eq_u32 s60, 28
	s_cselect_b32 s35, s15, s31
	s_cselect_b32 s34, s56, s30
	s_cselect_b32 s31, s13, s59
	s_cselect_b32 s30, s57, s58
	v_lshl_add_u64 v[216:217], s[28:29], 0, v[136:137]
	s_add_i32 m0, s25, 0xc000
	ds_read_b128 v[184:187], v153
	ds_read_b128 v[188:191], v153 offset:1024
	ds_read_b128 v[192:195], v153 offset:2048
	ds_read_b128 v[196:199], v153 offset:3072
	ds_read_b128 v[200:203], v153 offset:4096
	ds_read_b128 v[204:207], v153 offset:5120
	ds_read_b128 v[208:211], v153 offset:6144
	ds_read_b128 v[212:215], v153 offset:7168
	global_load_lds_dwordx4 v[216:217], off
	v_lshl_add_u64 v[216:217], s[28:29], 0, v[138:139]
	s_add_i32 m0, s25, 0xe000
	s_nop 0
	global_load_lds_dwordx4 v[216:217], off
	s_mov_b32 m0, s48
	s_nop 0
	global_load_lds_dwordx4 v[250:251], off
	s_mov_b32 m0, s49
	s_nop 0
	global_load_lds_dwordx4 v[252:253], off
	s_add_u32 s62, s30, 0x80000
	s_addc_u32 s63, s31, 0
	v_lshl_add_u64 v[216:217], s[30:31], 0, v[132:133]
	v_lshl_add_u64 v[218:219], s[30:31], 0, v[128:129]
	v_lshl_add_u64 v[246:247], s[62:63], 0, v[132:133]
	v_lshl_add_u64 v[222:223], s[34:35], 0, v[130:131]
	v_lshl_add_u64 v[248:249], s[62:63], 0, v[128:129]
	v_lshl_add_u64 v[220:221], s[34:35], 0, v[134:135]
	s_waitcnt vmcnt(10)
	s_waitcnt lgkmcnt(0)
	s_setprio 0
	s_barrier
	s_waitcnt lgkmcnt(0)
	v_mfma_f32_16x16x32_bf16 v[116:119], v[144:147], v[184:187], v[116:119]
	v_mfma_f32_16x16x32_bf16 v[112:115], v[160:163], v[184:187], v[112:115]
	v_mfma_f32_16x16x32_bf16 v[100:103], v[144:147], v[192:195], v[100:103]
	v_mfma_f32_16x16x32_bf16 v[96:99], v[160:163], v[192:195], v[96:99]
	v_mfma_f32_16x16x32_bf16 v[84:87], v[144:147], v[200:203], v[84:87]
	v_mfma_f32_16x16x32_bf16 v[80:83], v[160:163], v[200:203], v[80:83]
	v_mfma_f32_16x16x32_bf16 v[72:75], v[144:147], v[208:211], v[72:75]
	v_mfma_f32_16x16x32_bf16 v[68:71], v[160:163], v[208:211], v[68:71]
	v_mfma_f32_16x16x32_bf16 v[116:119], v[156:159], v[188:191], v[116:119]
	v_mfma_f32_16x16x32_bf16 v[112:115], v[164:167], v[188:191], v[112:115]
	v_mfma_f32_16x16x32_bf16 v[100:103], v[156:159], v[196:199], v[100:103]
	v_mfma_f32_16x16x32_bf16 v[96:99], v[164:167], v[196:199], v[96:99]
	v_mfma_f32_16x16x32_bf16 v[84:87], v[156:159], v[204:207], v[84:87]
	v_mfma_f32_16x16x32_bf16 v[80:83], v[164:167], v[204:207], v[80:83]
	v_mfma_f32_16x16x32_bf16 v[72:75], v[156:159], v[212:215], v[72:75]
	v_mfma_f32_16x16x32_bf16 v[68:71], v[164:167], v[212:215], v[68:71]
	v_mfma_f32_16x16x32_bf16 v[124:127], v[168:171], v[184:187], v[124:127]
	v_mfma_f32_16x16x32_bf16 v[120:123], v[176:179], v[184:187], v[120:123]
	v_mfma_f32_16x16x32_bf16 v[108:111], v[168:171], v[192:195], v[108:111]
	v_mfma_f32_16x16x32_bf16 v[104:107], v[176:179], v[192:195], v[104:107]
	v_mfma_f32_16x16x32_bf16 v[92:95], v[168:171], v[200:203], v[92:95]
	v_mfma_f32_16x16x32_bf16 v[88:91], v[176:179], v[200:203], v[88:91]
	v_mfma_f32_16x16x32_bf16 v[76:79], v[168:171], v[208:211], v[76:79]
	v_mfma_f32_16x16x32_bf16 v[64:67], v[176:179], v[208:211], v[64:67]
	v_mfma_f32_16x16x32_bf16 v[124:127], v[172:175], v[188:191], v[124:127]
	v_mfma_f32_16x16x32_bf16 v[120:123], v[180:183], v[188:191], v[120:123]
	v_mfma_f32_16x16x32_bf16 v[108:111], v[172:175], v[196:199], v[108:111]
	v_mfma_f32_16x16x32_bf16 v[104:107], v[180:183], v[196:199], v[104:107]
	v_mfma_f32_16x16x32_bf16 v[92:95], v[172:175], v[204:207], v[92:95]
	v_mfma_f32_16x16x32_bf16 v[88:91], v[180:183], v[204:207], v[88:91]
	v_mfma_f32_16x16x32_bf16 v[76:79], v[172:175], v[212:215], v[76:79]
	v_mfma_f32_16x16x32_bf16 v[64:67], v[180:183], v[212:215], v[64:67]
	s_barrier
	s_setprio 1
	s_add_i32 s61, s52, s42
	s_mov_b32 m0, s61
	s_nop 0
	global_load_lds_dwordx4 v[216:217], off
	s_add_i32 m0, s61, 0x2000
	s_add_i32 s61, s53, s42
	global_load_lds_dwordx4 v[218:219], off
	s_mov_b32 m0, s61
	s_nop 0
	global_load_lds_dwordx4 v[246:247], off
	s_add_i32 m0, s61, 0x2000
	s_nop 0
	global_load_lds_dwordx4 v[248:249], off
	ds_read_b128 v[184:187], v153 offset:16384
	ds_read_b128 v[188:191], v153 offset:17408
	ds_read_b128 v[192:195], v153 offset:18432
	ds_read_b128 v[196:199], v153 offset:19456
	ds_read_b128 v[200:203], v153 offset:20480
	ds_read_b128 v[204:207], v153 offset:21504
	ds_read_b128 v[208:211], v153 offset:22528
	ds_read_b128 v[212:215], v153 offset:23552
	s_waitcnt vmcnt(4)
	s_waitcnt lgkmcnt(0)
	s_setprio 0
	s_barrier
; #define PG8_STAGE(bufoff, gbase, voff) do { _Pragma("unroll") for (int _i = 0; _i < 2; ++_i) \
;         __builtin_amdgcn_global_load_lds((const unsigned*)((const char*)(gbase) + (voff)[_i]), (PG8_LAS unsigned*)(lds + (bufoff) + ldsw + _i * 8192), 16, 0, 0); } while (0)
; #define PG8_LDA(dst, b, h) do { _Pragma("unroll") for (int m = 0; m < 4; ++m) _Pragma("unroll") for (int k = 0; k < 2; ++k) dst[m][k] = *(const PG8_LAS bf16x8*)(lds + PG8_SA(b, h) + aoff + m * 2048 + k * 1024); } while (0)
; #define PG8_LDB(dst, b, h) do { _Pragma("unroll") for (int n = 0; n < 2; ++n) _Pragma("unroll") for (int k = 0; k < 2; ++k) dst[n][k] = *(const PG8_LAS bf16x8*)(lds + PG8_SB(b, h) + boff + n * 2048 + k * 1024); } while (0)
; #define PG8_MMA(ai, bj, At, Bt) do { __builtin_amdgcn_s_setprio(1); _Pragma("unroll") for (int m = 0; m < 4; ++m) _Pragma("unroll") for (int n = 0; n < 2; ++n) _Pragma("unroll") for (int k = 0; k < 2; ++k) \
;         acc[ai][bj][m][n] = __builtin_amdgcn_mfma_f32_16x16x32_bf16(Bt[n][k], At[m][k], acc[ai][bj][m][n], 0, 0, 0); __builtin_amdgcn_s_setprio(0); } while (0)
; #define PG8_WAIT_V(n) asm volatile("s_waitcnt vmcnt(" #n ")" ::: "memory")
; #define PG8_WAIT_L(n) asm volatile("s_waitcnt lgkmcnt(" #n ")" ::: "memory")
; #define PG8_BAR __builtin_amdgcn_s_barrier()
; #define PG8_SCHED __builtin_amdgcn_sched_barrier(0)
; template <class Epi, class Sched, bool ALIGN_EPI = false, bool SP2 = false>
; __device__ __forceinline__ void gemm_phase(PG8_LAS unsigned char* lds, const Gemm g, const Sched& S, const Epi& E) {
;     ...
;             PG8_WAIT_V(8); PG8_WAIT_L(0); PG8_BAR; PG8_MMA(1, 0, At, B0); PG8_MMA(1, 1, At, B1); PG8_BAR; PG8_SCHED;
;             PG8_LDB(B0, 1, 0); PG8_LDB(B1, 1, 1); PG8_SCHED; PG8_LDA(At, 1, 0); PG8_STAGE(PG8_SA(0, 1), a2 + hstep, voffA);
;             PG8_WAIT_V(8); PG8_WAIT_L(0); PG8_BAR; PG8_MMA(0, 0, At, B0); PG8_MMA(0, 1, At, B1); PG8_BAR; PG8_SCHED;
	s_waitcnt lgkmcnt(0)
	v_mfma_f32_16x16x32_bf16 v[56:59], v[144:147], v[184:187], v[56:59]
	v_mfma_f32_16x16x32_bf16 v[52:55], v[160:163], v[184:187], v[52:55]
	v_mfma_f32_16x16x32_bf16 v[40:43], v[144:147], v[192:195], v[40:43]
	v_mfma_f32_16x16x32_bf16 v[36:39], v[160:163], v[192:195], v[36:39]
	v_mfma_f32_16x16x32_bf16 v[24:27], v[144:147], v[200:203], v[24:27]
	v_mfma_f32_16x16x32_bf16 v[20:23], v[160:163], v[200:203], v[20:23]
	v_mfma_f32_16x16x32_bf16 v[8:11], v[144:147], v[208:211], v[8:11]
	v_mfma_f32_16x16x32_bf16 v[0:3], v[160:163], v[208:211], v[0:3]
	v_mfma_f32_16x16x32_bf16 v[56:59], v[156:159], v[188:191], v[56:59]
	v_mfma_f32_16x16x32_bf16 v[52:55], v[164:167], v[188:191], v[52:55]
	v_mfma_f32_16x16x32_bf16 v[40:43], v[156:159], v[196:199], v[40:43]
	v_mfma_f32_16x16x32_bf16 v[36:39], v[164:167], v[196:199], v[36:39]
	v_mfma_f32_16x16x32_bf16 v[24:27], v[156:159], v[204:207], v[24:27]
	v_mfma_f32_16x16x32_bf16 v[20:23], v[164:167], v[204:207], v[20:23]
	v_mfma_f32_16x16x32_bf16 v[8:11], v[156:159], v[212:215], v[8:11]
	v_mfma_f32_16x16x32_bf16 v[0:3], v[164:167], v[212:215], v[0:3]
	v_mfma_f32_16x16x32_bf16 v[60:63], v[168:171], v[184:187], v[60:63]
	v_mfma_f32_16x16x32_bf16 v[48:51], v[176:179], v[184:187], v[48:51]
	v_mfma_f32_16x16x32_bf16 v[44:47], v[168:171], v[192:195], v[44:47]
	v_mfma_f32_16x16x32_bf16 v[32:35], v[176:179], v[192:195], v[32:35]
	v_mfma_f32_16x16x32_bf16 v[28:31], v[168:171], v[200:203], v[28:31]
	v_mfma_f32_16x16x32_bf16 v[16:19], v[176:179], v[200:203], v[16:19]
	v_mfma_f32_16x16x32_bf16 v[12:15], v[168:171], v[208:211], v[12:15]
	v_mfma_f32_16x16x32_bf16 v[4:7], v[176:179], v[208:211], v[4:7]
	v_mfma_f32_16x16x32_bf16 v[60:63], v[172:175], v[188:191], v[60:63]
	v_mfma_f32_16x16x32_bf16 v[48:51], v[180:183], v[188:191], v[48:51]
	v_mfma_f32_16x16x32_bf16 v[44:47], v[172:175], v[196:199], v[44:47]
	v_mfma_f32_16x16x32_bf16 v[32:35], v[180:183], v[196:199], v[32:35]
	v_mfma_f32_16x16x32_bf16 v[28:31], v[172:175], v[204:207], v[28:31]
	v_mfma_f32_16x16x32_bf16 v[16:19], v[180:183], v[204:207], v[16:19]
	v_mfma_f32_16x16x32_bf16 v[12:15], v[172:175], v[212:215], v[12:15]
	v_mfma_f32_16x16x32_bf16 v[4:7], v[180:183], v[212:215], v[4:7]
	s_barrier
	s_setprio 1
	s_add_i32 s61, 0, 0x18000
	v_add_u32_e32 v155, s61, v149
	s_add_i32 s62, 0, 0x1c000
	ds_read_b128 v[144:147], v155
	ds_read_b128 v[156:159], v155 offset:1024
	ds_read_b128 v[160:163], v155 offset:2048
	ds_read_b128 v[164:167], v155 offset:3072
	v_add_u32_e32 v155, s62, v149
	ds_read_b128 v[168:171], v155
	ds_read_b128 v[172:175], v155 offset:1024
	ds_read_b128 v[176:179], v155 offset:2048
	ds_read_b128 v[180:183], v155 offset:3072
	s_add_u32 s34, s34, 0x80000
	s_addc_u32 s35, s35, 0
	s_mov_b32 m0, s46
	v_lshl_add_u64 v[224:225], s[34:35], 0, v[134:135]
	ds_read_b128 v[184:187], v153 offset:32768
	ds_read_b128 v[188:191], v153 offset:33792
	ds_read_b128 v[192:195], v153 offset:34816
	ds_read_b128 v[196:199], v153 offset:35840
	ds_read_b128 v[200:203], v153 offset:36864
	ds_read_b128 v[204:207], v153 offset:37888
	ds_read_b128 v[208:211], v153 offset:38912
	ds_read_b128 v[212:215], v153 offset:39936
	global_load_lds_dwordx4 v[224:225], off
	v_lshl_add_u64 v[224:225], s[34:35], 0, v[130:131]
	s_mov_b32 m0, s47
	s_nop 0
	global_load_lds_dwordx4 v[224:225], off
	s_mov_b32 m0, s25
	s_nop 0
	global_load_lds_dwordx4 v[220:221], off
	s_mov_b32 m0, s45
	s_nop 0
	global_load_lds_dwordx4 v[222:223], off
	s_add_u32 s30, s30, 0x80080
	s_addc_u32 s31, s31, 0
	v_lshl_add_u64 v[216:217], v[216:217], 0, s[8:9]
	v_lshl_add_u64 v[218:219], v[218:219], 0, s[8:9]
	v_lshl_add_u64 v[246:247], s[30:31], 0, v[132:133]
	v_lshl_add_u64 v[248:249], s[30:31], 0, v[128:129]
	v_lshl_add_u64 v[250:251], v[220:221], 0, s[8:9]
	v_lshl_add_u64 v[252:253], v[222:223], 0, s[8:9]
	s_waitcnt vmcnt(10)
	s_waitcnt lgkmcnt(0)
	s_setprio 0
	s_barrier
; #define PG8_STAGE(bufoff, gbase, voff) do { _Pragma("unroll") for (int _i = 0; _i < 2; ++_i) \
;         __builtin_amdgcn_global_load_lds((const unsigned*)((const char*)(gbase) + (voff)[_i]), (PG8_LAS unsigned*)(lds + (bufoff) + ldsw + _i * 8192), 16, 0, 0); } while (0)
; #define PG8_LDA(dst, b, h) do { _Pragma("unroll") for (int m = 0; m < 4; ++m) _Pragma("unroll") for (int k = 0; k < 2; ++k) dst[m][k] = *(const PG8_LAS bf16x8*)(lds + PG8_SA(b, h) + aoff + m * 2048 + k * 1024); } while (0)
; #define PG8_MMA(ai, bj, At, Bt) do { __builtin_amdgcn_s_setprio(1); _Pragma("unroll") for (int m = 0; m < 4; ++m) _Pragma("unroll") for (int n = 0; n < 2; ++n) _Pragma("unroll") for (int k = 0; k < 2; ++k) \
;         acc[ai][bj][m][n] = __builtin_amdgcn_mfma_f32_16x16x32_bf16(Bt[n][k], At[m][k], acc[ai][bj][m][n], 0, 0, 0); __builtin_amdgcn_s_setprio(0); } while (0)
; #define PG8_WAIT_V(n) asm volatile("s_waitcnt vmcnt(" #n ")" ::: "memory")
; #define PG8_WAIT_L(n) asm volatile("s_waitcnt lgkmcnt(" #n ")" ::: "memory")
; #define PG8_BAR __builtin_amdgcn_s_barrier()
; #define PG8_SCHED __builtin_amdgcn_sched_barrier(0)
; template <class Epi, class Sched, bool ALIGN_EPI = false, bool SP2 = false>
; __device__ __forceinline__ void gemm_phase(PG8_LAS unsigned char* lds, const Gemm g, const Sched& S, const Epi& E) {
;     ...
;             PG8_WAIT_V(8); PG8_WAIT_L(0); PG8_BAR; PG8_MMA(0, 0, At, B0); PG8_MMA(0, 1, At, B1); PG8_BAR; PG8_SCHED;
;             PG8_LDA(At, 1, 1); PG8_STAGE(PG8_SB(1, 0), b3, voffB); PG8_STAGE(PG8_SB(1, 1), b3 + hstep, voffB); PG8_STAGE(PG8_SA(1, 0), a3, voffA);
;             PG8_WAIT_V(8); PG8_WAIT_L(0); PG8_BAR; PG8_MMA(1, 0, At, B0); PG8_MMA(1, 1, At, B1); PG8_BAR; PG8_SCHED;
	s_waitcnt lgkmcnt(0)
	v_mfma_f32_16x16x32_bf16 v[116:119], v[144:147], v[184:187], v[116:119]
	v_mfma_f32_16x16x32_bf16 v[112:115], v[160:163], v[184:187], v[112:115]
	v_mfma_f32_16x16x32_bf16 v[100:103], v[144:147], v[192:195], v[100:103]
	v_mfma_f32_16x16x32_bf16 v[96:99], v[160:163], v[192:195], v[96:99]
	v_mfma_f32_16x16x32_bf16 v[84:87], v[144:147], v[200:203], v[84:87]
	v_mfma_f32_16x16x32_bf16 v[80:83], v[160:163], v[200:203], v[80:83]
	v_mfma_f32_16x16x32_bf16 v[72:75], v[144:147], v[208:211], v[72:75]
	v_mfma_f32_16x16x32_bf16 v[68:71], v[160:163], v[208:211], v[68:71]
	v_mfma_f32_16x16x32_bf16 v[116:119], v[156:159], v[188:191], v[116:119]
	v_mfma_f32_16x16x32_bf16 v[112:115], v[164:167], v[188:191], v[112:115]
	v_mfma_f32_16x16x32_bf16 v[100:103], v[156:159], v[196:199], v[100:103]
	v_mfma_f32_16x16x32_bf16 v[96:99], v[164:167], v[196:199], v[96:99]
	v_mfma_f32_16x16x32_bf16 v[84:87], v[156:159], v[204:207], v[84:87]
	v_mfma_f32_16x16x32_bf16 v[80:83], v[164:167], v[204:207], v[80:83]
	v_mfma_f32_16x16x32_bf16 v[72:75], v[156:159], v[212:215], v[72:75]
	v_mfma_f32_16x16x32_bf16 v[68:71], v[164:167], v[212:215], v[68:71]
	v_mfma_f32_16x16x32_bf16 v[124:127], v[168:171], v[184:187], v[124:127]
	v_mfma_f32_16x16x32_bf16 v[120:123], v[176:179], v[184:187], v[120:123]
	v_mfma_f32_16x16x32_bf16 v[108:111], v[168:171], v[192:195], v[108:111]
	v_mfma_f32_16x16x32_bf16 v[104:107], v[176:179], v[192:195], v[104:107]
	v_mfma_f32_16x16x32_bf16 v[92:95], v[168:171], v[200:203], v[92:95]
	v_mfma_f32_16x16x32_bf16 v[88:91], v[176:179], v[200:203], v[88:91]
	v_mfma_f32_16x16x32_bf16 v[76:79], v[168:171], v[208:211], v[76:79]
	v_mfma_f32_16x16x32_bf16 v[64:67], v[176:179], v[208:211], v[64:67]
	v_mfma_f32_16x16x32_bf16 v[124:127], v[172:175], v[188:191], v[124:127]
	v_mfma_f32_16x16x32_bf16 v[120:123], v[180:183], v[188:191], v[120:123]
	v_mfma_f32_16x16x32_bf16 v[108:111], v[172:175], v[196:199], v[108:111]
	v_mfma_f32_16x16x32_bf16 v[104:107], v[180:183], v[196:199], v[104:107]
	v_mfma_f32_16x16x32_bf16 v[92:95], v[172:175], v[204:207], v[92:95]
	v_mfma_f32_16x16x32_bf16 v[88:91], v[180:183], v[204:207], v[88:91]
	v_mfma_f32_16x16x32_bf16 v[76:79], v[172:175], v[212:215], v[76:79]
	v_mfma_f32_16x16x32_bf16 v[64:67], v[180:183], v[212:215], v[64:67]
	s_barrier
	s_setprio 1
	s_add_i32 s34, s61, s42
	s_mov_b32 m0, s34
	s_nop 0
	global_load_lds_dwordx4 v[216:217], off
	s_add_i32 m0, s34, 0x2000
	s_add_i32 s34, s62, s42
	global_load_lds_dwordx4 v[218:219], off
	s_mov_b32 m0, s34
	s_nop 0
	global_load_lds_dwordx4 v[246:247], off
	s_add_i32 m0, s34, 0x2000
	s_nop 0
	global_load_lds_dwordx4 v[248:249], off
	ds_read_b128 v[184:187], v153 offset:49152
	ds_read_b128 v[188:191], v153 offset:50176
	ds_read_b128 v[192:195], v153 offset:51200
	ds_read_b128 v[196:199], v153 offset:52224
	ds_read_b128 v[200:203], v153 offset:53248
	ds_read_b128 v[204:207], v153 offset:54272
	ds_read_b128 v[208:211], v153 offset:55296
	ds_read_b128 v[212:215], v153 offset:56320
	s_waitcnt vmcnt(4)
	s_waitcnt lgkmcnt(0)
	s_setprio 0
	s_barrier
	s_waitcnt lgkmcnt(0)
	v_mfma_f32_16x16x32_bf16 v[56:59], v[144:147], v[184:187], v[56:59]
	v_mfma_f32_16x16x32_bf16 v[52:55], v[160:163], v[184:187], v[52:55]
	v_mfma_f32_16x16x32_bf16 v[40:43], v[144:147], v[192:195], v[40:43]
	v_mfma_f32_16x16x32_bf16 v[36:39], v[160:163], v[192:195], v[36:39]
	v_mfma_f32_16x16x32_bf16 v[24:27], v[144:147], v[200:203], v[24:27]
	v_mfma_f32_16x16x32_bf16 v[20:23], v[160:163], v[200:203], v[20:23]
	v_mfma_f32_16x16x32_bf16 v[8:11], v[144:147], v[208:211], v[8:11]
	v_mfma_f32_16x16x32_bf16 v[0:3], v[160:163], v[208:211], v[0:3]
	v_mfma_f32_16x16x32_bf16 v[56:59], v[156:159], v[188:191], v[56:59]
	v_mfma_f32_16x16x32_bf16 v[52:55], v[164:167], v[188:191], v[52:55]
	v_mfma_f32_16x16x32_bf16 v[40:43], v[156:159], v[196:199], v[40:43]
	v_mfma_f32_16x16x32_bf16 v[36:39], v[164:167], v[196:199], v[36:39]
	v_mfma_f32_16x16x32_bf16 v[24:27], v[156:159], v[204:207], v[24:27]
	v_mfma_f32_16x16x32_bf16 v[20:23], v[164:167], v[204:207], v[20:23]
	v_mfma_f32_16x16x32_bf16 v[8:11], v[156:159], v[212:215], v[8:11]
	v_mfma_f32_16x16x32_bf16 v[0:3], v[164:167], v[212:215], v[0:3]
	v_mfma_f32_16x16x32_bf16 v[60:63], v[168:171], v[184:187], v[60:63]
	v_mfma_f32_16x16x32_bf16 v[48:51], v[176:179], v[184:187], v[48:51]
	v_mfma_f32_16x16x32_bf16 v[44:47], v[168:171], v[192:195], v[44:47]
	v_mfma_f32_16x16x32_bf16 v[32:35], v[176:179], v[192:195], v[32:35]
	v_mfma_f32_16x16x32_bf16 v[28:31], v[168:171], v[200:203], v[28:31]
	v_mfma_f32_16x16x32_bf16 v[16:19], v[176:179], v[200:203], v[16:19]
	v_mfma_f32_16x16x32_bf16 v[12:15], v[168:171], v[208:211], v[12:15]
	v_mfma_f32_16x16x32_bf16 v[4:7], v[176:179], v[208:211], v[4:7]
	v_mfma_f32_16x16x32_bf16 v[60:63], v[172:175], v[188:191], v[60:63]
	v_mfma_f32_16x16x32_bf16 v[48:51], v[180:183], v[188:191], v[48:51]
	v_mfma_f32_16x16x32_bf16 v[44:47], v[172:175], v[196:199], v[44:47]
	v_mfma_f32_16x16x32_bf16 v[32:35], v[180:183], v[196:199], v[32:35]
	v_mfma_f32_16x16x32_bf16 v[28:31], v[172:175], v[204:207], v[28:31]
	v_mfma_f32_16x16x32_bf16 v[16:19], v[180:183], v[204:207], v[16:19]
	v_mfma_f32_16x16x32_bf16 v[12:15], v[172:175], v[212:215], v[12:15]
	v_mfma_f32_16x16x32_bf16 v[4:7], v[180:183], v[212:215], v[4:7]
	s_barrier
	s_add_i32 s60, s60, 2
	s_add_u32 s28, s28, 0x100
	s_addc_u32 s29, s29, 0
	s_add_u32 s58, s58, 0x100
	s_addc_u32 s59, s59, 0
	s_cmp_gt_u32 s60, 29
	s_cbranch_scc0 .LBB0_705
	s_and_b64 vcc, exec, s[10:11]
	s_cbranch_vccz .LBB0_708
	s_barrier

; #define PG8_STAGE(bufoff, gbase, voff) do { _Pragma("unroll") for (int _i = 0; _i < 2; ++_i) \
;         __builtin_amdgcn_global_load_lds((const unsigned*)((const char*)(gbase) + (voff)[_i]), (PG8_LAS unsigned*)(lds + (bufoff) + ldsw + _i * 8192), 16, 0, 0); } while (0)
; #define PG8_LDA(dst, b, h) do { _Pragma("unroll") for (int m = 0; m < 4; ++m) _Pragma("unroll") for (int k = 0; k < 2; ++k) dst[m][k] = *(const PG8_LAS bf16x8*)(lds + PG8_SA(b, h) + aoff + m * 2048 + k * 1024); } while (0)
; #define PG8_LDB(dst, b, h) do { _Pragma("unroll") for (int n = 0; n < 2; ++n) _Pragma("unroll") for (int k = 0; k < 2; ++k) dst[n][k] = *(const PG8_LAS bf16x8*)(lds + PG8_SB(b, h) + boff + n * 2048 + k * 1024); } while (0)
; #define PG8_MMA(ai, bj, At, Bt) do { __builtin_amdgcn_s_setprio(1); _Pragma("unroll") for (int m = 0; m < 4; ++m) _Pragma("unroll") for (int n = 0; n < 2; ++n) _Pragma("unroll") for (int k = 0; k < 2; ++k) \
;         acc[ai][bj][m][n] = __builtin_amdgcn_mfma_f32_16x16x32_bf16(Bt[n][k], At[m][k], acc[ai][bj][m][n], 0, 0, 0); __builtin_amdgcn_s_setprio(0); } while (0)
; #define PG8_WAIT_V(n) asm volatile("s_waitcnt vmcnt(" #n ")" ::: "memory")
; #define PG8_WAIT_L(n) asm volatile("s_waitcnt lgkmcnt(" #n ")" ::: "memory")
; template <class Epi, class Sched, bool ALIGN_EPI = false, bool SP2 = false>
; __device__ __forceinline__ void gemm_phase(PG8_LAS unsigned char* lds, const Gemm g, const Sched& S, const Epi& E) {
;     ...
;             const bool last = (t == nt - 2);
;             const char* a1 = cA + (size_t)(t + 1) * kstep;
;             const char* a2 = last ? nA : cA + (size_t)(t + 2) * kstep; const char* b2 = last ? nB : cB + (size_t)(t + 2) * kstep;
;             const char* a3 = a2 + kstep; const char* b3 = b2 + kstep;
;             if (last && has_next) S.a_ready(nxt);
;             if constexpr (SP2) {
;             PG8_LDB(B0, 0, 0); PG8_LDB(B1, 0, 1); PG8_SCHED; PG8_LDA(At, 0, 0); PG8_STAGE(PG8_SA(1, 1), a1 + hstep, voffA);
;             PG8_WAIT_V(8); PG8_WAIT_L(0); PG8_BAR; PG8_MMA(0, 0, At, B0); PG8_MMA(0, 1, At, B1); PG8_BAR; PG8_SCHED;
;             PG8_LDA(At, 0, 1); PG8_STAGE(PG8_SB(0, 0), b2, voffB); PG8_STAGE(PG8_SB(0, 1), b2 + hstep, voffB); PG8_STAGE(PG8_SA(0, 0), a2, voffA);
;             PG8_WAIT_V(8); PG8_WAIT_L(0); PG8_BAR; PG8_MMA(1, 0, At, B0); PG8_MMA(1, 1, At, B1); PG8_BAR; PG8_SCHED;
.LBB0_788:
	s_setprio 1
	ds_read_b128 v[128:131], v189
	ds_read_b128 v[132:135], v189 offset:1024
	ds_read_b128 v[136:139], v189 offset:2048
	ds_read_b128 v[140:143], v189 offset:3072
	ds_read_b128 v[144:147], v190
	ds_read_b128 v[148:151], v190 offset:1024
	ds_read_b128 v[168:171], v190 offset:2048
	ds_read_b128 v[172:175], v190 offset:3072
	s_add_u32 s24, s22, 0x100
	s_addc_u32 s25, s23, 0
	s_cmpk_eq_i32 s58, 0x54
	s_cselect_b32 s31, s7, s25
	s_cselect_b32 s30, s6, s24
	s_cselect_b32 s29, s17, s57
	s_cselect_b32 s28, s16, s56
	v_lshl_add_u64 v[184:185], s[22:23], 0, v[160:161]
	s_add_i32 m0, s40, 0xc000
	ds_read_b128 v[176:179], v191
	ds_read_b128 v[180:183], v191 offset:1024
	ds_read_b128 v[192:195], v191 offset:2048
	ds_read_b128 v[196:199], v191 offset:3072
	ds_read_b128 v[200:203], v191 offset:4096
	ds_read_b128 v[204:207], v191 offset:5120
	ds_read_b128 v[208:211], v191 offset:6144
	ds_read_b128 v[212:215], v191 offset:7168
	global_load_lds_dwordx4 v[184:185], off
	v_lshl_add_u64 v[184:185], s[22:23], 0, v[162:163]
	s_add_i32 m0, s40, 0xe000
	s_nop 0
	global_load_lds_dwordx4 v[184:185], off
	s_mov_b32 m0, s45
	s_nop 0
	global_load_lds_dwordx4 v[250:251], off
	s_mov_b32 m0, s46
	s_nop 0
	global_load_lds_dwordx4 v[252:253], off
	s_add_u32 s22, s28, 0x160000
	s_addc_u32 s23, s29, 0
	v_lshl_add_u64 v[184:185], s[28:29], 0, v[154:155]
	v_lshl_add_u64 v[216:217], s[28:29], 0, v[158:159]
	v_lshl_add_u64 v[246:247], s[22:23], 0, v[154:155]
	v_lshl_add_u64 v[220:221], s[30:31], 0, v[156:157]
	v_lshl_add_u64 v[248:249], s[22:23], 0, v[158:159]
	v_lshl_add_u64 v[218:219], s[30:31], 0, v[152:153]
	s_waitcnt vmcnt(10)
	s_waitcnt lgkmcnt(0)
	s_setprio 0
	s_barrier
	s_waitcnt lgkmcnt(0)
	v_mfma_f32_16x16x32_bf16 v[124:127], v[128:131], v[176:179], v[124:127]
	v_mfma_f32_16x16x32_bf16 v[120:123], v[136:139], v[176:179], v[120:123]
	v_mfma_f32_16x16x32_bf16 v[108:111], v[128:131], v[192:195], v[108:111]
	v_mfma_f32_16x16x32_bf16 v[104:107], v[136:139], v[192:195], v[104:107]
	v_mfma_f32_16x16x32_bf16 v[92:95], v[128:131], v[200:203], v[92:95]
	v_mfma_f32_16x16x32_bf16 v[88:91], v[136:139], v[200:203], v[88:91]
	v_mfma_f32_16x16x32_bf16 v[76:79], v[128:131], v[208:211], v[76:79]
	v_mfma_f32_16x16x32_bf16 v[72:75], v[136:139], v[208:211], v[72:75]
	v_mfma_f32_16x16x32_bf16 v[124:127], v[132:135], v[180:183], v[124:127]
	v_mfma_f32_16x16x32_bf16 v[120:123], v[140:143], v[180:183], v[120:123]
	v_mfma_f32_16x16x32_bf16 v[108:111], v[132:135], v[196:199], v[108:111]
	v_mfma_f32_16x16x32_bf16 v[104:107], v[140:143], v[196:199], v[104:107]
	v_mfma_f32_16x16x32_bf16 v[92:95], v[132:135], v[204:207], v[92:95]
	v_mfma_f32_16x16x32_bf16 v[88:91], v[140:143], v[204:207], v[88:91]
	v_mfma_f32_16x16x32_bf16 v[76:79], v[132:135], v[212:215], v[76:79]
	v_mfma_f32_16x16x32_bf16 v[72:75], v[140:143], v[212:215], v[72:75]
	v_mfma_f32_16x16x32_bf16 v[116:119], v[144:147], v[176:179], v[116:119]
	v_mfma_f32_16x16x32_bf16 v[112:115], v[168:171], v[176:179], v[112:115]
	v_mfma_f32_16x16x32_bf16 v[100:103], v[144:147], v[192:195], v[100:103]
	v_mfma_f32_16x16x32_bf16 v[96:99], v[168:171], v[192:195], v[96:99]
	v_mfma_f32_16x16x32_bf16 v[84:87], v[144:147], v[200:203], v[84:87]
	v_mfma_f32_16x16x32_bf16 v[80:83], v[168:171], v[200:203], v[80:83]
	v_mfma_f32_16x16x32_bf16 v[68:71], v[144:147], v[208:211], v[68:71]
	v_mfma_f32_16x16x32_bf16 v[64:67], v[168:171], v[208:211], v[64:67]
	v_mfma_f32_16x16x32_bf16 v[116:119], v[148:151], v[180:183], v[116:119]
	v_mfma_f32_16x16x32_bf16 v[112:115], v[172:175], v[180:183], v[112:115]
	v_mfma_f32_16x16x32_bf16 v[100:103], v[148:151], v[196:199], v[100:103]
	v_mfma_f32_16x16x32_bf16 v[96:99], v[172:175], v[196:199], v[96:99]
	v_mfma_f32_16x16x32_bf16 v[84:87], v[148:151], v[204:207], v[84:87]
	v_mfma_f32_16x16x32_bf16 v[80:83], v[172:175], v[204:207], v[80:83]
	v_mfma_f32_16x16x32_bf16 v[68:71], v[148:151], v[212:215], v[68:71]
	v_mfma_f32_16x16x32_bf16 v[64:67], v[172:175], v[212:215], v[64:67]
	s_barrier
	s_setprio 1
	s_add_i32 s22, s49, s39
	s_mov_b32 m0, s22
	s_nop 0
	global_load_lds_dwordx4 v[184:185], off
	s_add_i32 m0, s22, 0x2000
	s_add_i32 s59, s50, s39
	global_load_lds_dwordx4 v[216:217], off
	s_mov_b32 m0, s59
	s_nop 0
	global_load_lds_dwordx4 v[246:247], off
	s_add_i32 m0, s59, 0x2000
	s_nop 0
	global_load_lds_dwordx4 v[248:249], off
	ds_read_b128 v[176:179], v191 offset:16384
	ds_read_b128 v[180:183], v191 offset:17408
	ds_read_b128 v[192:195], v191 offset:18432
	ds_read_b128 v[196:199], v191 offset:19456
	ds_read_b128 v[200:203], v191 offset:20480
	ds_read_b128 v[204:207], v191 offset:21504
	ds_read_b128 v[208:211], v191 offset:22528
	ds_read_b128 v[212:215], v191 offset:23552
	s_waitcnt vmcnt(4)
	s_waitcnt lgkmcnt(0)
	s_setprio 0
	s_barrier
; #define PG8_STAGE(bufoff, gbase, voff) do { _Pragma("unroll") for (int _i = 0; _i < 2; ++_i) \
;         __builtin_amdgcn_global_load_lds((const unsigned*)((const char*)(gbase) + (voff)[_i]), (PG8_LAS unsigned*)(lds + (bufoff) + ldsw + _i * 8192), 16, 0, 0); } while (0)
; #define PG8_LDA(dst, b, h) do { _Pragma("unroll") for (int m = 0; m < 4; ++m) _Pragma("unroll") for (int k = 0; k < 2; ++k) dst[m][k] = *(const PG8_LAS bf16x8*)(lds + PG8_SA(b, h) + aoff + m * 2048 + k * 1024); } while (0)
; #define PG8_LDB(dst, b, h) do { _Pragma("unroll") for (int n = 0; n < 2; ++n) _Pragma("unroll") for (int k = 0; k < 2; ++k) dst[n][k] = *(const PG8_LAS bf16x8*)(lds + PG8_SB(b, h) + boff + n * 2048 + k * 1024); } while (0)
; #define PG8_MMA(ai, bj, At, Bt) do { __builtin_amdgcn_s_setprio(1); _Pragma("unroll") for (int m = 0; m < 4; ++m) _Pragma("unroll") for (int n = 0; n < 2; ++n) _Pragma("unroll") for (int k = 0; k < 2; ++k) \
;         acc[ai][bj][m][n] = __builtin_amdgcn_mfma_f32_16x16x32_bf16(Bt[n][k], At[m][k], acc[ai][bj][m][n], 0, 0, 0); __builtin_amdgcn_s_setprio(0); } while (0)
; #define PG8_WAIT_V(n) asm volatile("s_waitcnt vmcnt(" #n ")" ::: "memory")
; #define PG8_WAIT_L(n) asm volatile("s_waitcnt lgkmcnt(" #n ")" ::: "memory")
; #define PG8_BAR __builtin_amdgcn_s_barrier()
; #define PG8_SCHED __builtin_amdgcn_sched_barrier(0)
; template <class Epi, class Sched, bool ALIGN_EPI = false, bool SP2 = false>
; __device__ __forceinline__ void gemm_phase(PG8_LAS unsigned char* lds, const Gemm g, const Sched& S, const Epi& E) {
;     ...
;             PG8_WAIT_V(8); PG8_WAIT_L(0); PG8_BAR; PG8_MMA(1, 0, At, B0); PG8_MMA(1, 1, At, B1); PG8_BAR; PG8_SCHED;
;             PG8_LDB(B0, 1, 0); PG8_LDB(B1, 1, 1); PG8_SCHED; PG8_LDA(At, 1, 0); PG8_STAGE(PG8_SA(0, 1), a2 + hstep, voffA);
;             PG8_WAIT_V(8); PG8_WAIT_L(0); PG8_BAR; PG8_MMA(0, 0, At, B0); PG8_MMA(0, 1, At, B1); PG8_BAR; PG8_SCHED;
	s_waitcnt lgkmcnt(0)
	v_mfma_f32_16x16x32_bf16 v[60:63], v[128:131], v[176:179], v[60:63]
	v_mfma_f32_16x16x32_bf16 v[56:59], v[136:139], v[176:179], v[56:59]
	v_mfma_f32_16x16x32_bf16 v[44:47], v[128:131], v[192:195], v[44:47]
	v_mfma_f32_16x16x32_bf16 v[40:43], v[136:139], v[192:195], v[40:43]
	v_mfma_f32_16x16x32_bf16 v[28:31], v[128:131], v[200:203], v[28:31]
	v_mfma_f32_16x16x32_bf16 v[24:27], v[136:139], v[200:203], v[24:27]
	v_mfma_f32_16x16x32_bf16 v[12:15], v[128:131], v[208:211], v[12:15]
	v_mfma_f32_16x16x32_bf16 v[8:11], v[136:139], v[208:211], v[8:11]
	v_mfma_f32_16x16x32_bf16 v[60:63], v[132:135], v[180:183], v[60:63]
	v_mfma_f32_16x16x32_bf16 v[56:59], v[140:143], v[180:183], v[56:59]
	v_mfma_f32_16x16x32_bf16 v[44:47], v[132:135], v[196:199], v[44:47]
	v_mfma_f32_16x16x32_bf16 v[40:43], v[140:143], v[196:199], v[40:43]
	v_mfma_f32_16x16x32_bf16 v[28:31], v[132:135], v[204:207], v[28:31]
	v_mfma_f32_16x16x32_bf16 v[24:27], v[140:143], v[204:207], v[24:27]
	v_mfma_f32_16x16x32_bf16 v[12:15], v[132:135], v[212:215], v[12:15]
	v_mfma_f32_16x16x32_bf16 v[8:11], v[140:143], v[212:215], v[8:11]
	v_mfma_f32_16x16x32_bf16 v[52:55], v[144:147], v[176:179], v[52:55]
	v_mfma_f32_16x16x32_bf16 v[48:51], v[168:171], v[176:179], v[48:51]
	v_mfma_f32_16x16x32_bf16 v[36:39], v[144:147], v[192:195], v[36:39]
	v_mfma_f32_16x16x32_bf16 v[32:35], v[168:171], v[192:195], v[32:35]
	v_mfma_f32_16x16x32_bf16 v[20:23], v[144:147], v[200:203], v[20:23]
	v_mfma_f32_16x16x32_bf16 v[16:19], v[168:171], v[200:203], v[16:19]
	v_mfma_f32_16x16x32_bf16 v[4:7], v[144:147], v[208:211], v[4:7]
	v_mfma_f32_16x16x32_bf16 v[0:3], v[168:171], v[208:211], v[0:3]
	v_mfma_f32_16x16x32_bf16 v[52:55], v[148:151], v[180:183], v[52:55]
	v_mfma_f32_16x16x32_bf16 v[48:51], v[172:175], v[180:183], v[48:51]
	v_mfma_f32_16x16x32_bf16 v[36:39], v[148:151], v[196:199], v[36:39]
	v_mfma_f32_16x16x32_bf16 v[32:35], v[172:175], v[196:199], v[32:35]
	v_mfma_f32_16x16x32_bf16 v[20:23], v[148:151], v[204:207], v[20:23]
	v_mfma_f32_16x16x32_bf16 v[16:19], v[172:175], v[204:207], v[16:19]
	v_mfma_f32_16x16x32_bf16 v[4:7], v[148:151], v[212:215], v[4:7]
	v_mfma_f32_16x16x32_bf16 v[0:3], v[172:175], v[212:215], v[0:3]
	s_barrier
	s_setprio 1
	s_add_i32 s59, 0, 0x18000
	s_add_i32 s60, 0, 0x1c000
	v_add_u32_e32 v140, s59, v187
	v_add_u32_e32 v172, s60, v187
	ds_read_b128 v[128:131], v140
	ds_read_b128 v[132:135], v140 offset:1024
	ds_read_b128 v[136:139], v140 offset:2048
	ds_read_b128 v[140:143], v140 offset:3072
	ds_read_b128 v[144:147], v172
	ds_read_b128 v[148:151], v172 offset:1024
	ds_read_b128 v[168:171], v172 offset:2048
	ds_read_b128 v[172:175], v172 offset:3072
	s_add_u32 s22, s30, 0x160000
	s_addc_u32 s23, s31, 0
	s_mov_b32 m0, s42
	v_lshl_add_u64 v[222:223], s[22:23], 0, v[152:153]
	ds_read_b128 v[176:179], v191 offset:32768
	ds_read_b128 v[180:183], v191 offset:33792
	ds_read_b128 v[192:195], v191 offset:34816
	ds_read_b128 v[196:199], v191 offset:35840
	ds_read_b128 v[200:203], v191 offset:36864
	ds_read_b128 v[204:207], v191 offset:37888
	ds_read_b128 v[208:211], v191 offset:38912
	ds_read_b128 v[212:215], v191 offset:39936
	global_load_lds_dwordx4 v[222:223], off
	v_lshl_add_u64 v[222:223], s[22:23], 0, v[156:157]
	s_mov_b32 m0, s43
	s_nop 0
	global_load_lds_dwordx4 v[222:223], off
	s_mov_b32 m0, s40
	s_nop 0
	global_load_lds_dwordx4 v[218:219], off
	s_mov_b32 m0, s41
	s_nop 0
	global_load_lds_dwordx4 v[220:221], off
	s_add_u32 s22, s28, 0x160080
	s_addc_u32 s23, s29, 0
	v_lshl_add_u64 v[184:185], v[184:185], 0, s[12:13]
	v_lshl_add_u64 v[216:217], v[216:217], 0, s[12:13]
	v_lshl_add_u64 v[246:247], s[22:23], 0, v[154:155]
	v_lshl_add_u64 v[248:249], s[22:23], 0, v[158:159]
	v_lshl_add_u64 v[250:251], v[218:219], 0, s[12:13]
	v_lshl_add_u64 v[252:253], v[220:221], 0, s[12:13]
	s_waitcnt vmcnt(10)
	s_waitcnt lgkmcnt(0)
	s_setprio 0
	s_barrier
; #define PG8_STAGE(bufoff, gbase, voff) do { _Pragma("unroll") for (int _i = 0; _i < 2; ++_i) \
;         __builtin_amdgcn_global_load_lds((const unsigned*)((const char*)(gbase) + (voff)[_i]), (PG8_LAS unsigned*)(lds + (bufoff) + ldsw + _i * 8192), 16, 0, 0); } while (0)
; #define PG8_LDA(dst, b, h) do { _Pragma("unroll") for (int m = 0; m < 4; ++m) _Pragma("unroll") for (int k = 0; k < 2; ++k) dst[m][k] = *(const PG8_LAS bf16x8*)(lds + PG8_SA(b, h) + aoff + m * 2048 + k * 1024); } while (0)
; #define PG8_MMA(ai, bj, At, Bt) do { __builtin_amdgcn_s_setprio(1); _Pragma("unroll") for (int m = 0; m < 4; ++m) _Pragma("unroll") for (int n = 0; n < 2; ++n) _Pragma("unroll") for (int k = 0; k < 2; ++k) \
;         acc[ai][bj][m][n] = __builtin_amdgcn_mfma_f32_16x16x32_bf16(Bt[n][k], At[m][k], acc[ai][bj][m][n], 0, 0, 0); __builtin_amdgcn_s_setprio(0); } while (0)
; #define PG8_WAIT_V(n) asm volatile("s_waitcnt vmcnt(" #n ")" ::: "memory")
; #define PG8_WAIT_L(n) asm volatile("s_waitcnt lgkmcnt(" #n ")" ::: "memory")
; #define PG8_BAR __builtin_amdgcn_s_barrier()
; #define PG8_SCHED __builtin_amdgcn_sched_barrier(0)
; template <class Epi, class Sched, bool ALIGN_EPI = false, bool SP2 = false>
; __device__ __forceinline__ void gemm_phase(PG8_LAS unsigned char* lds, const Gemm g, const Sched& S, const Epi& E) {
;     ...
;             PG8_WAIT_V(8); PG8_WAIT_L(0); PG8_BAR; PG8_MMA(0, 0, At, B0); PG8_MMA(0, 1, At, B1); PG8_BAR; PG8_SCHED;
;             PG8_LDA(At, 1, 1); PG8_STAGE(PG8_SB(1, 0), b3, voffB); PG8_STAGE(PG8_SB(1, 1), b3 + hstep, voffB); PG8_STAGE(PG8_SA(1, 0), a3, voffA);
;             PG8_WAIT_V(8); PG8_WAIT_L(0); PG8_BAR; PG8_MMA(1, 0, At, B0); PG8_MMA(1, 1, At, B1); PG8_BAR; PG8_SCHED;
	s_waitcnt lgkmcnt(0)
	v_mfma_f32_16x16x32_bf16 v[124:127], v[128:131], v[176:179], v[124:127]
	v_mfma_f32_16x16x32_bf16 v[120:123], v[136:139], v[176:179], v[120:123]
	v_mfma_f32_16x16x32_bf16 v[108:111], v[128:131], v[192:195], v[108:111]
	v_mfma_f32_16x16x32_bf16 v[104:107], v[136:139], v[192:195], v[104:107]
	v_mfma_f32_16x16x32_bf16 v[92:95], v[128:131], v[200:203], v[92:95]
	v_mfma_f32_16x16x32_bf16 v[88:91], v[136:139], v[200:203], v[88:91]
	v_mfma_f32_16x16x32_bf16 v[76:79], v[128:131], v[208:211], v[76:79]
	v_mfma_f32_16x16x32_bf16 v[72:75], v[136:139], v[208:211], v[72:75]
	v_mfma_f32_16x16x32_bf16 v[124:127], v[132:135], v[180:183], v[124:127]
	v_mfma_f32_16x16x32_bf16 v[120:123], v[140:143], v[180:183], v[120:123]
	v_mfma_f32_16x16x32_bf16 v[108:111], v[132:135], v[196:199], v[108:111]
	v_mfma_f32_16x16x32_bf16 v[104:107], v[140:143], v[196:199], v[104:107]
	v_mfma_f32_16x16x32_bf16 v[92:95], v[132:135], v[204:207], v[92:95]
	v_mfma_f32_16x16x32_bf16 v[88:91], v[140:143], v[204:207], v[88:91]
	v_mfma_f32_16x16x32_bf16 v[76:79], v[132:135], v[212:215], v[76:79]
	v_mfma_f32_16x16x32_bf16 v[72:75], v[140:143], v[212:215], v[72:75]
	v_mfma_f32_16x16x32_bf16 v[116:119], v[144:147], v[176:179], v[116:119]
	v_mfma_f32_16x16x32_bf16 v[112:115], v[168:171], v[176:179], v[112:115]
	v_mfma_f32_16x16x32_bf16 v[100:103], v[144:147], v[192:195], v[100:103]
	v_mfma_f32_16x16x32_bf16 v[96:99], v[168:171], v[192:195], v[96:99]
	v_mfma_f32_16x16x32_bf16 v[84:87], v[144:147], v[200:203], v[84:87]
	v_mfma_f32_16x16x32_bf16 v[80:83], v[168:171], v[200:203], v[80:83]
	v_mfma_f32_16x16x32_bf16 v[68:71], v[144:147], v[208:211], v[68:71]
	v_mfma_f32_16x16x32_bf16 v[64:67], v[168:171], v[208:211], v[64:67]
	v_mfma_f32_16x16x32_bf16 v[116:119], v[148:151], v[180:183], v[116:119]
	v_mfma_f32_16x16x32_bf16 v[112:115], v[172:175], v[180:183], v[112:115]
	v_mfma_f32_16x16x32_bf16 v[100:103], v[148:151], v[196:199], v[100:103]
	v_mfma_f32_16x16x32_bf16 v[96:99], v[172:175], v[196:199], v[96:99]
	v_mfma_f32_16x16x32_bf16 v[84:87], v[148:151], v[204:207], v[84:87]
	v_mfma_f32_16x16x32_bf16 v[80:83], v[172:175], v[204:207], v[80:83]
	v_mfma_f32_16x16x32_bf16 v[68:71], v[148:151], v[212:215], v[68:71]
	v_mfma_f32_16x16x32_bf16 v[64:67], v[172:175], v[212:215], v[64:67]
	s_barrier
	s_setprio 1
	s_add_i32 s22, s59, s39
	s_mov_b32 m0, s22
	s_nop 0
	global_load_lds_dwordx4 v[184:185], off
	s_add_i32 m0, s22, 0x2000
	s_add_i32 s28, s60, s39
	global_load_lds_dwordx4 v[216:217], off
	s_mov_b32 m0, s28
	s_nop 0
	global_load_lds_dwordx4 v[246:247], off
	s_add_i32 m0, s28, 0x2000
	s_nop 0
	global_load_lds_dwordx4 v[248:249], off
	ds_read_b128 v[176:179], v191 offset:49152
	ds_read_b128 v[180:183], v191 offset:50176
	ds_read_b128 v[192:195], v191 offset:51200
	ds_read_b128 v[196:199], v191 offset:52224
	ds_read_b128 v[200:203], v191 offset:53248
	ds_read_b128 v[204:207], v191 offset:54272
	ds_read_b128 v[208:211], v191 offset:55296
	ds_read_b128 v[212:215], v191 offset:56320
	s_waitcnt vmcnt(4)
	s_waitcnt lgkmcnt(0)
	s_setprio 0
	s_barrier
	s_waitcnt lgkmcnt(0)
	v_mfma_f32_16x16x32_bf16 v[60:63], v[128:131], v[176:179], v[60:63]
	v_mfma_f32_16x16x32_bf16 v[56:59], v[136:139], v[176:179], v[56:59]
	v_mfma_f32_16x16x32_bf16 v[44:47], v[128:131], v[192:195], v[44:47]
	v_mfma_f32_16x16x32_bf16 v[40:43], v[136:139], v[192:195], v[40:43]
	v_mfma_f32_16x16x32_bf16 v[28:31], v[128:131], v[200:203], v[28:31]
	v_mfma_f32_16x16x32_bf16 v[24:27], v[136:139], v[200:203], v[24:27]
	v_mfma_f32_16x16x32_bf16 v[12:15], v[128:131], v[208:211], v[12:15]
	v_mfma_f32_16x16x32_bf16 v[8:11], v[136:139], v[208:211], v[8:11]
	v_mfma_f32_16x16x32_bf16 v[60:63], v[132:135], v[180:183], v[60:63]
	v_mfma_f32_16x16x32_bf16 v[56:59], v[140:143], v[180:183], v[56:59]
	v_mfma_f32_16x16x32_bf16 v[44:47], v[132:135], v[196:199], v[44:47]
	v_mfma_f32_16x16x32_bf16 v[40:43], v[140:143], v[196:199], v[40:43]
	v_mfma_f32_16x16x32_bf16 v[28:31], v[132:135], v[204:207], v[28:31]
	v_mfma_f32_16x16x32_bf16 v[24:27], v[140:143], v[204:207], v[24:27]
	v_mfma_f32_16x16x32_bf16 v[12:15], v[132:135], v[212:215], v[12:15]
	v_mfma_f32_16x16x32_bf16 v[8:11], v[140:143], v[212:215], v[8:11]
	v_mfma_f32_16x16x32_bf16 v[52:55], v[144:147], v[176:179], v[52:55]
	v_mfma_f32_16x16x32_bf16 v[48:51], v[168:171], v[176:179], v[48:51]
	v_mfma_f32_16x16x32_bf16 v[36:39], v[144:147], v[192:195], v[36:39]
	v_mfma_f32_16x16x32_bf16 v[32:35], v[168:171], v[192:195], v[32:35]
	v_mfma_f32_16x16x32_bf16 v[20:23], v[144:147], v[200:203], v[20:23]
	v_mfma_f32_16x16x32_bf16 v[16:19], v[168:171], v[200:203], v[16:19]
	v_mfma_f32_16x16x32_bf16 v[4:7], v[144:147], v[208:211], v[4:7]
	v_mfma_f32_16x16x32_bf16 v[0:3], v[168:171], v[208:211], v[0:3]
	v_mfma_f32_16x16x32_bf16 v[52:55], v[148:151], v[180:183], v[52:55]
	v_mfma_f32_16x16x32_bf16 v[48:51], v[172:175], v[180:183], v[48:51]
	v_mfma_f32_16x16x32_bf16 v[36:39], v[148:151], v[196:199], v[36:39]
	v_mfma_f32_16x16x32_bf16 v[32:35], v[172:175], v[196:199], v[32:35]
	v_mfma_f32_16x16x32_bf16 v[20:23], v[148:151], v[204:207], v[20:23]
	v_mfma_f32_16x16x32_bf16 v[16:19], v[172:175], v[204:207], v[16:19]
	v_mfma_f32_16x16x32_bf16 v[4:7], v[148:151], v[212:215], v[4:7]
	v_mfma_f32_16x16x32_bf16 v[0:3], v[172:175], v[212:215], v[0:3]
	s_barrier
	s_add_i32 s58, s58, 2
	s_add_u32 s56, s56, 0x100
	s_addc_u32 s57, s57, 0
	s_cmpk_gt_u32 s58, 0x55
	s_mov_b64 s[22:23], s[24:25]
	s_cbranch_scc0 .LBB0_788
	s_and_b64 vcc, exec, s[14:15]
	s_cbranch_vccz .LBB0_791
	s_barrier
